# scan D1b: 4 operand sets, chunk barrier moved to step 63 with next-chunk prefetch, packed ops spaced further from their consumers
# speedup vs baseline: 1.0416x; 1.0021x over previous
.LBB0_56:
	s_and_b64 s[4:5], s[42:43], exec
	s_mov_b32 s4, 0x1caf0000
	s_cselect_b32 s4, s4, 0x14af0000
	s_add_u32 s4, s30, s4
	s_addc_u32 s5, s31, 0
	s_lshl_b32 s6, s37, 1
	v_lshl_add_u32 v0, s64, 4, v58
	s_add_u32 s4, s4, s6
	s_addc_u32 s5, s5, 0
	v_ashrrev_i32_e32 v1, 31, v0
	s_waitcnt lgkmcnt(0)
	s_barrier
	v_lshl_add_u64 v[0:1], v[0:1], 1, s[4:5]
	s_and_b64 s[4:5], s[42:43], exec
	s_movk_i32 s4, 0x4000
	s_mov_b32 s28, 0
	s_cselect_b32 s85, 0, -1
	s_cselect_b32 s84, s4, 0xffffc000
	s_waitcnt vmcnt(0)
	v_mov_b32_e32 v6, 0
	v_mov_b32_e32 v4, v78
	v_mov_b32_e32 v5, v15
	v_mov_b32_e32 v7, 0
	v_mov_b32_e32 v8, 0
	v_mov_b32_e32 v9, 0
	v_lshlrev_b32_e32 v74, 4, v58
	v_add_u32_e32 v74, 0x20100, v74
	v_mov_b32_e32 v10, v59
	v_mov_b32_e32 v11, v74
	ds_read_b128 v[66:69], v11 offset:0
	ds_read_b128 v[20:23], v10 offset:256
	ds_read_b128 v[16:19], v10 offset:0
	ds_read_b128 v[28:31], v10 offset:768
	ds_read_b128 v[24:27], v10 offset:512
	ds_read_b128 v[36:39], v10 offset:1280
	ds_read_b128 v[32:35], v10 offset:1024
	ds_read_b128 v[44:47], v10 offset:1792
	ds_read_b128 v[40:43], v10 offset:1536
.Lscan_cons_chunk:
	v_cndmask_b32_e64 v2, v4, v5, s[42:43]
	v_add_lshl_u32 v2, v2, s80, 10
	v_mov_b32_e32 v3, v180
	s_add_i32 s28, s28, 0x10000
	v_lshl_add_u64 v[2:3], v[0:1], 0, v[2:3]
	v_add_u32_e32 v5, 64, v5
	v_subrev_u32_e32 v4, 64, v4
	s_waitcnt lgkmcnt(4)
	v_fma_mix_f32 v12, v6, v20, v180 op_sel_hi:[0,1,0]
	v_fma_mix_f32 v12, v7, v20, v12 op_sel:[0,1,0] op_sel_hi:[0,1,0]
	v_fma_mix_f32 v12, v8, v21, v12 op_sel_hi:[0,1,0]
	v_fma_mix_f32 v12, v9, v21, v12 op_sel:[0,1,0] op_sel_hi:[0,1,0]
	v_pk_mul_f32 v[48:49], v[6:7], v[16:17]
	v_pk_mul_f32 v[50:51], v[8:9], v[18:19]
	v_add_f32_dpp v12, v12, v12 row_ror:1 row_mask:0xf bank_mask:0xf bound_ctrl:1
	s_nop 1
	v_add_f32_dpp v12, v12, v12 row_ror:2 row_mask:0xf bank_mask:0xf bound_ctrl:1
	v_pk_fma_f32 v[48:49], v[28:29], v[66:67], v[48:49] op_sel_hi:[1,0,1]
	v_pk_fma_f32 v[50:51], v[30:31], v[66:67], v[50:51] op_sel_hi:[1,0,1]
	v_add_f32_dpp v12, v12, v12 row_ror:4 row_mask:0xf bank_mask:0xf bound_ctrl:1
	s_nop 1
	v_add_f32_dpp v12, v12, v12 row_ror:8 row_mask:0xf bank_mask:0xf bound_ctrl:1
	v_pk_fma_f32 v[6:7], v[24:25], v[12:13], v[48:49] op_sel_hi:[1,0,1] neg_lo:[1,0,0] neg_hi:[1,0,0]
	v_pk_fma_f32 v[8:9], v[26:27], v[12:13], v[50:51] op_sel_hi:[1,0,1] neg_lo:[1,0,0] neg_hi:[1,0,0]
	ds_read_b128 v[88:91], v10 offset:2304
	ds_read_b128 v[84:87], v10 offset:2048
	ds_read_b128 v[96:99], v10 offset:2816
	ds_read_b128 v[92:95], v10 offset:2560
	s_waitcnt lgkmcnt(4)
	v_fma_mix_f32 v12, v6, v36, v180 op_sel_hi:[0,1,0]
	v_fma_mix_f32 v12, v7, v36, v12 op_sel:[0,1,0] op_sel_hi:[0,1,0]
	v_fma_mix_f32 v12, v8, v37, v12 op_sel_hi:[0,1,0]
	v_fma_mix_f32 v12, v9, v37, v12 op_sel:[0,1,0] op_sel_hi:[0,1,0]
	v_pk_mul_f32 v[48:49], v[6:7], v[32:33]
	v_pk_mul_f32 v[50:51], v[8:9], v[34:35]
	v_add_f32_dpp v12, v12, v12 row_ror:1 row_mask:0xf bank_mask:0xf bound_ctrl:1
	v_fma_mix_f32 v52, v6, v22, v180 op_sel_hi:[0,1,0]
	v_fma_mix_f32 v52, v7, v22, v52 op_sel:[0,1,0] op_sel_hi:[0,1,0]
	v_add_f32_dpp v12, v12, v12 row_ror:2 row_mask:0xf bank_mask:0xf bound_ctrl:1
	v_pk_fma_f32 v[48:49], v[44:45], v[66:67], v[48:49] op_sel:[0,1,0]
	v_pk_fma_f32 v[50:51], v[46:47], v[66:67], v[50:51] op_sel:[0,1,0]
	v_add_f32_dpp v12, v12, v12 row_ror:4 row_mask:0xf bank_mask:0xf bound_ctrl:1
	v_fma_mix_f32 v52, v8, v23, v52 op_sel_hi:[0,1,0]
	v_fma_mix_f32 v52, v9, v23, v52 op_sel:[0,1,0] op_sel_hi:[0,1,0]
	v_add_f32_dpp v12, v12, v12 row_ror:8 row_mask:0xf bank_mask:0xf bound_ctrl:1
	v_pk_fma_f32 v[6:7], v[40:41], v[12:13], v[48:49] op_sel_hi:[1,0,1] neg_lo:[1,0,0] neg_hi:[1,0,0]
	v_pk_fma_f32 v[8:9], v[42:43], v[12:13], v[50:51] op_sel_hi:[1,0,1] neg_lo:[1,0,0] neg_hi:[1,0,0]
	ds_read_b128 v[110:113], v10 offset:3328
	ds_read_b128 v[106:109], v10 offset:3072
	ds_read_b128 v[118:121], v10 offset:3840
	ds_read_b128 v[114:117], v10 offset:3584
	ds_read_b128 v[70:73], v11 offset:256
	s_waitcnt lgkmcnt(5)
	v_fma_mix_f32 v12, v6, v88, v180 op_sel_hi:[0,1,0]
	v_fma_mix_f32 v12, v7, v88, v12 op_sel:[0,1,0] op_sel_hi:[0,1,0]
	v_fma_mix_f32 v12, v8, v89, v12 op_sel_hi:[0,1,0]
	v_fma_mix_f32 v12, v9, v89, v12 op_sel:[0,1,0] op_sel_hi:[0,1,0]
	v_pk_mul_f32 v[48:49], v[6:7], v[84:85]
	v_pk_mul_f32 v[50:51], v[8:9], v[86:87]
	v_add_f32_dpp v12, v12, v12 row_ror:1 row_mask:0xf bank_mask:0xf bound_ctrl:1
	v_fma_mix_f32 v53, v6, v38, v180 op_sel_hi:[0,1,0]
	v_fma_mix_f32 v53, v7, v38, v53 op_sel:[0,1,0] op_sel_hi:[0,1,0]
	v_add_f32_dpp v12, v12, v12 row_ror:2 row_mask:0xf bank_mask:0xf bound_ctrl:1
	v_pk_fma_f32 v[48:49], v[96:97], v[68:69], v[48:49] op_sel_hi:[1,0,1]
	v_pk_fma_f32 v[50:51], v[98:99], v[68:69], v[50:51] op_sel_hi:[1,0,1]
	v_add_f32_dpp v12, v12, v12 row_ror:4 row_mask:0xf bank_mask:0xf bound_ctrl:1
	v_fma_mix_f32 v53, v8, v39, v53 op_sel_hi:[0,1,0]
	v_fma_mix_f32 v53, v9, v39, v53 op_sel:[0,1,0] op_sel_hi:[0,1,0]
	v_add_f32_dpp v12, v12, v12 row_ror:8 row_mask:0xf bank_mask:0xf bound_ctrl:1
	v_pk_fma_f32 v[6:7], v[92:93], v[12:13], v[48:49] op_sel_hi:[1,0,1] neg_lo:[1,0,0] neg_hi:[1,0,0]
	v_pk_fma_f32 v[8:9], v[94:95], v[12:13], v[50:51] op_sel_hi:[1,0,1] neg_lo:[1,0,0] neg_hi:[1,0,0]
	ds_read_b128 v[20:23], v10 offset:4352
	ds_read_b128 v[16:19], v10 offset:4096
	ds_read_b128 v[28:31], v10 offset:4864
	ds_read_b128 v[24:27], v10 offset:4608
	s_waitcnt lgkmcnt(5)
	v_fma_mix_f32 v12, v6, v110, v180 op_sel_hi:[0,1,0]
	v_fma_mix_f32 v12, v7, v110, v12 op_sel:[0,1,0] op_sel_hi:[0,1,0]
	v_fma_mix_f32 v12, v8, v111, v12 op_sel_hi:[0,1,0]
	v_fma_mix_f32 v12, v9, v111, v12 op_sel:[0,1,0] op_sel_hi:[0,1,0]
	v_pk_mul_f32 v[48:49], v[6:7], v[106:107]
	v_pk_mul_f32 v[50:51], v[8:9], v[108:109]
	v_add_f32_dpp v12, v12, v12 row_ror:1 row_mask:0xf bank_mask:0xf bound_ctrl:1
	v_fma_mix_f32 v54, v6, v90, v180 op_sel_hi:[0,1,0]
	v_fma_mix_f32 v54, v7, v90, v54 op_sel:[0,1,0] op_sel_hi:[0,1,0]
	v_add_f32_dpp v12, v12, v12 row_ror:2 row_mask:0xf bank_mask:0xf bound_ctrl:1
	v_pk_fma_f32 v[48:49], v[118:119], v[68:69], v[48:49] op_sel:[0,1,0]
	v_pk_fma_f32 v[50:51], v[120:121], v[68:69], v[50:51] op_sel:[0,1,0]
	v_add_f32_dpp v12, v12, v12 row_ror:4 row_mask:0xf bank_mask:0xf bound_ctrl:1
	v_fma_mix_f32 v54, v8, v91, v54 op_sel_hi:[0,1,0]
	v_fma_mix_f32 v54, v9, v91, v54 op_sel:[0,1,0] op_sel_hi:[0,1,0]
	v_add_f32_dpp v12, v12, v12 row_ror:8 row_mask:0xf bank_mask:0xf bound_ctrl:1
	v_pk_fma_f32 v[6:7], v[114:115], v[12:13], v[48:49] op_sel_hi:[1,0,1] neg_lo:[1,0,0] neg_hi:[1,0,0]
	v_pk_fma_f32 v[8:9], v[116:117], v[12:13], v[50:51] op_sel_hi:[1,0,1] neg_lo:[1,0,0] neg_hi:[1,0,0]
	ds_read_b128 v[36:39], v10 offset:5376
	ds_read_b128 v[32:35], v10 offset:5120
	ds_read_b128 v[44:47], v10 offset:5888
	ds_read_b128 v[40:43], v10 offset:5632
	s_waitcnt lgkmcnt(4)
	v_fma_mix_f32 v12, v6, v20, v180 op_sel_hi:[0,1,0]
	v_fma_mix_f32 v12, v7, v20, v12 op_sel:[0,1,0] op_sel_hi:[0,1,0]
	v_fma_mix_f32 v12, v8, v21, v12 op_sel_hi:[0,1,0]
	v_fma_mix_f32 v12, v9, v21, v12 op_sel:[0,1,0] op_sel_hi:[0,1,0]
	v_pk_mul_f32 v[48:49], v[6:7], v[16:17]
	v_pk_mul_f32 v[50:51], v[8:9], v[18:19]
	v_add_f32_dpp v12, v12, v12 row_ror:1 row_mask:0xf bank_mask:0xf bound_ctrl:1
	v_fma_mix_f32 v55, v6, v112, v180 op_sel_hi:[0,1,0]
	v_fma_mix_f32 v55, v7, v112, v55 op_sel:[0,1,0] op_sel_hi:[0,1,0]
	v_add_f32_dpp v12, v12, v12 row_ror:2 row_mask:0xf bank_mask:0xf bound_ctrl:1
	v_pk_fma_f32 v[48:49], v[28:29], v[70:71], v[48:49] op_sel_hi:[1,0,1]
	v_pk_fma_f32 v[50:51], v[30:31], v[70:71], v[50:51] op_sel_hi:[1,0,1]
	v_add_f32_dpp v12, v12, v12 row_ror:4 row_mask:0xf bank_mask:0xf bound_ctrl:1
	v_fma_mix_f32 v55, v8, v113, v55 op_sel_hi:[0,1,0]
	v_fma_mix_f32 v55, v9, v113, v55 op_sel:[0,1,0] op_sel_hi:[0,1,0]
	v_add_f32_dpp v12, v12, v12 row_ror:8 row_mask:0xf bank_mask:0xf bound_ctrl:1
	v_pk_fma_f32 v[6:7], v[24:25], v[12:13], v[48:49] op_sel_hi:[1,0,1] neg_lo:[1,0,0] neg_hi:[1,0,0]
	v_pk_fma_f32 v[8:9], v[26:27], v[12:13], v[50:51] op_sel_hi:[1,0,1] neg_lo:[1,0,0] neg_hi:[1,0,0]
	ds_read_b128 v[88:91], v10 offset:6400
	ds_read_b128 v[84:87], v10 offset:6144
	ds_read_b128 v[96:99], v10 offset:6912
	ds_read_b128 v[92:95], v10 offset:6656
	s_waitcnt lgkmcnt(4)
	v_fma_mix_f32 v12, v6, v36, v180 op_sel_hi:[0,1,0]
	v_fma_mix_f32 v12, v7, v36, v12 op_sel:[0,1,0] op_sel_hi:[0,1,0]
	v_fma_mix_f32 v12, v8, v37, v12 op_sel_hi:[0,1,0]
	v_fma_mix_f32 v12, v9, v37, v12 op_sel:[0,1,0] op_sel_hi:[0,1,0]
	v_pk_mul_f32 v[48:49], v[6:7], v[32:33]
	v_pk_mul_f32 v[50:51], v[8:9], v[34:35]
	v_add_f32_dpp v12, v12, v12 row_ror:1 row_mask:0xf bank_mask:0xf bound_ctrl:1
	v_fma_mix_f32 v56, v6, v22, v180 op_sel_hi:[0,1,0]
	v_fma_mix_f32 v56, v7, v22, v56 op_sel:[0,1,0] op_sel_hi:[0,1,0]
	v_add_f32_dpp v12, v12, v12 row_ror:2 row_mask:0xf bank_mask:0xf bound_ctrl:1
	v_pk_fma_f32 v[48:49], v[44:45], v[70:71], v[48:49] op_sel:[0,1,0]
	v_pk_fma_f32 v[50:51], v[46:47], v[70:71], v[50:51] op_sel:[0,1,0]
	v_add_f32_dpp v12, v12, v12 row_ror:4 row_mask:0xf bank_mask:0xf bound_ctrl:1
	v_fma_mix_f32 v56, v8, v23, v56 op_sel_hi:[0,1,0]
	v_fma_mix_f32 v56, v9, v23, v56 op_sel:[0,1,0] op_sel_hi:[0,1,0]
	v_add_f32_dpp v12, v12, v12 row_ror:8 row_mask:0xf bank_mask:0xf bound_ctrl:1
	v_pk_fma_f32 v[6:7], v[40:41], v[12:13], v[48:49] op_sel_hi:[1,0,1] neg_lo:[1,0,0] neg_hi:[1,0,0]
	v_pk_fma_f32 v[8:9], v[42:43], v[12:13], v[50:51] op_sel_hi:[1,0,1] neg_lo:[1,0,0] neg_hi:[1,0,0]
	ds_read_b128 v[110:113], v10 offset:7424
	ds_read_b128 v[106:109], v10 offset:7168
	ds_read_b128 v[118:121], v10 offset:7936
	ds_read_b128 v[114:117], v10 offset:7680
	ds_read_b128 v[66:69], v11 offset:512
	s_waitcnt lgkmcnt(5)
	v_fma_mix_f32 v12, v6, v88, v180 op_sel_hi:[0,1,0]
	v_fma_mix_f32 v12, v7, v88, v12 op_sel:[0,1,0] op_sel_hi:[0,1,0]
	v_fma_mix_f32 v12, v8, v89, v12 op_sel_hi:[0,1,0]
	v_fma_mix_f32 v12, v9, v89, v12 op_sel:[0,1,0] op_sel_hi:[0,1,0]
	v_pk_mul_f32 v[48:49], v[6:7], v[84:85]
	v_pk_mul_f32 v[50:51], v[8:9], v[86:87]
	v_add_f32_dpp v12, v12, v12 row_ror:1 row_mask:0xf bank_mask:0xf bound_ctrl:1
	v_fma_mix_f32 v57, v6, v38, v180 op_sel_hi:[0,1,0]
	v_fma_mix_f32 v57, v7, v38, v57 op_sel:[0,1,0] op_sel_hi:[0,1,0]
	v_add_f32_dpp v12, v12, v12 row_ror:2 row_mask:0xf bank_mask:0xf bound_ctrl:1
	v_pk_fma_f32 v[48:49], v[96:97], v[72:73], v[48:49] op_sel_hi:[1,0,1]
	v_pk_fma_f32 v[50:51], v[98:99], v[72:73], v[50:51] op_sel_hi:[1,0,1]
	v_add_f32_dpp v12, v12, v12 row_ror:4 row_mask:0xf bank_mask:0xf bound_ctrl:1
	v_fma_mix_f32 v57, v8, v39, v57 op_sel_hi:[0,1,0]
	v_fma_mix_f32 v57, v9, v39, v57 op_sel:[0,1,0] op_sel_hi:[0,1,0]
	v_add_f32_dpp v12, v12, v12 row_ror:8 row_mask:0xf bank_mask:0xf bound_ctrl:1
	v_pk_fma_f32 v[6:7], v[92:93], v[12:13], v[48:49] op_sel_hi:[1,0,1] neg_lo:[1,0,0] neg_hi:[1,0,0]
	v_pk_fma_f32 v[8:9], v[94:95], v[12:13], v[50:51] op_sel_hi:[1,0,1] neg_lo:[1,0,0] neg_hi:[1,0,0]
	ds_read_b128 v[20:23], v10 offset:8448
	ds_read_b128 v[16:19], v10 offset:8192
	ds_read_b128 v[28:31], v10 offset:8960
	ds_read_b128 v[24:27], v10 offset:8704
	s_waitcnt lgkmcnt(5)
	v_fma_mix_f32 v12, v6, v110, v180 op_sel_hi:[0,1,0]
	v_fma_mix_f32 v12, v7, v110, v12 op_sel:[0,1,0] op_sel_hi:[0,1,0]
	v_fma_mix_f32 v12, v8, v111, v12 op_sel_hi:[0,1,0]
	v_fma_mix_f32 v12, v9, v111, v12 op_sel:[0,1,0] op_sel_hi:[0,1,0]
	v_pk_mul_f32 v[48:49], v[6:7], v[106:107]
	v_pk_mul_f32 v[50:51], v[8:9], v[108:109]
	v_add_f32_dpp v12, v12, v12 row_ror:1 row_mask:0xf bank_mask:0xf bound_ctrl:1
	v_fma_mix_f32 v81, v6, v90, v180 op_sel_hi:[0,1,0]
	v_fma_mix_f32 v81, v7, v90, v81 op_sel:[0,1,0] op_sel_hi:[0,1,0]
	v_add_f32_dpp v12, v12, v12 row_ror:2 row_mask:0xf bank_mask:0xf bound_ctrl:1
	v_pk_fma_f32 v[48:49], v[118:119], v[72:73], v[48:49] op_sel:[0,1,0]
	v_pk_fma_f32 v[50:51], v[120:121], v[72:73], v[50:51] op_sel:[0,1,0]
	v_add_f32_dpp v12, v12, v12 row_ror:4 row_mask:0xf bank_mask:0xf bound_ctrl:1
	v_fma_mix_f32 v81, v8, v91, v81 op_sel_hi:[0,1,0]
	v_fma_mix_f32 v81, v9, v91, v81 op_sel:[0,1,0] op_sel_hi:[0,1,0]
	v_add_f32_dpp v12, v12, v12 row_ror:8 row_mask:0xf bank_mask:0xf bound_ctrl:1
	v_pk_fma_f32 v[6:7], v[114:115], v[12:13], v[48:49] op_sel_hi:[1,0,1] neg_lo:[1,0,0] neg_hi:[1,0,0]
	v_pk_fma_f32 v[8:9], v[116:117], v[12:13], v[50:51] op_sel_hi:[1,0,1] neg_lo:[1,0,0] neg_hi:[1,0,0]
	ds_read_b128 v[36:39], v10 offset:9472
	ds_read_b128 v[32:35], v10 offset:9216
	ds_read_b128 v[44:47], v10 offset:9984
	ds_read_b128 v[40:43], v10 offset:9728
	s_waitcnt lgkmcnt(4)
	v_fma_mix_f32 v12, v6, v20, v180 op_sel_hi:[0,1,0]
	v_fma_mix_f32 v12, v7, v20, v12 op_sel:[0,1,0] op_sel_hi:[0,1,0]
	v_fma_mix_f32 v12, v8, v21, v12 op_sel_hi:[0,1,0]
	v_fma_mix_f32 v12, v9, v21, v12 op_sel:[0,1,0] op_sel_hi:[0,1,0]
	v_pk_mul_f32 v[48:49], v[6:7], v[16:17]
	v_pk_mul_f32 v[50:51], v[8:9], v[18:19]
	v_add_f32_dpp v12, v12, v12 row_ror:1 row_mask:0xf bank_mask:0xf bound_ctrl:1
	v_fma_mix_f32 v82, v6, v112, v180 op_sel_hi:[0,1,0]
	v_fma_mix_f32 v82, v7, v112, v82 op_sel:[0,1,0] op_sel_hi:[0,1,0]
	v_add_f32_dpp v12, v12, v12 row_ror:2 row_mask:0xf bank_mask:0xf bound_ctrl:1
	v_pk_fma_f32 v[48:49], v[28:29], v[66:67], v[48:49] op_sel_hi:[1,0,1]
	v_pk_fma_f32 v[50:51], v[30:31], v[66:67], v[50:51] op_sel_hi:[1,0,1]
	v_add_f32_dpp v12, v12, v12 row_ror:4 row_mask:0xf bank_mask:0xf bound_ctrl:1
	v_fma_mix_f32 v82, v8, v113, v82 op_sel_hi:[0,1,0]
	v_fma_mix_f32 v82, v9, v113, v82 op_sel:[0,1,0] op_sel_hi:[0,1,0]
	v_add_f32_dpp v12, v12, v12 row_ror:8 row_mask:0xf bank_mask:0xf bound_ctrl:1
	v_pk_fma_f32 v[6:7], v[24:25], v[12:13], v[48:49] op_sel_hi:[1,0,1] neg_lo:[1,0,0] neg_hi:[1,0,0]
	v_pk_fma_f32 v[8:9], v[26:27], v[12:13], v[50:51] op_sel_hi:[1,0,1] neg_lo:[1,0,0] neg_hi:[1,0,0]
	ds_read_b128 v[88:91], v10 offset:10496
	ds_read_b128 v[84:87], v10 offset:10240
	ds_read_b128 v[96:99], v10 offset:11008
	ds_read_b128 v[92:95], v10 offset:10752
	s_waitcnt lgkmcnt(4)
	v_fma_mix_f32 v12, v6, v36, v180 op_sel_hi:[0,1,0]
	v_fma_mix_f32 v12, v7, v36, v12 op_sel:[0,1,0] op_sel_hi:[0,1,0]
	v_fma_mix_f32 v12, v8, v37, v12 op_sel_hi:[0,1,0]
	v_fma_mix_f32 v12, v9, v37, v12 op_sel:[0,1,0] op_sel_hi:[0,1,0]
	v_pk_mul_f32 v[48:49], v[6:7], v[32:33]
	v_pk_mul_f32 v[50:51], v[8:9], v[34:35]
	v_add_f32_dpp v12, v12, v12 row_ror:1 row_mask:0xf bank_mask:0xf bound_ctrl:1
	v_fma_mix_f32 v83, v6, v22, v180 op_sel_hi:[0,1,0]
	v_fma_mix_f32 v83, v7, v22, v83 op_sel:[0,1,0] op_sel_hi:[0,1,0]
	v_add_f32_dpp v12, v12, v12 row_ror:2 row_mask:0xf bank_mask:0xf bound_ctrl:1
	v_pk_fma_f32 v[48:49], v[44:45], v[66:67], v[48:49] op_sel:[0,1,0]
	v_pk_fma_f32 v[50:51], v[46:47], v[66:67], v[50:51] op_sel:[0,1,0]
	v_add_f32_dpp v12, v12, v12 row_ror:4 row_mask:0xf bank_mask:0xf bound_ctrl:1
	v_fma_mix_f32 v83, v8, v23, v83 op_sel_hi:[0,1,0]
	v_fma_mix_f32 v83, v9, v23, v83 op_sel:[0,1,0] op_sel_hi:[0,1,0]
	v_add_f32_dpp v12, v12, v12 row_ror:8 row_mask:0xf bank_mask:0xf bound_ctrl:1
	v_pk_fma_f32 v[6:7], v[40:41], v[12:13], v[48:49] op_sel_hi:[1,0,1] neg_lo:[1,0,0] neg_hi:[1,0,0]
	v_pk_fma_f32 v[8:9], v[42:43], v[12:13], v[50:51] op_sel_hi:[1,0,1] neg_lo:[1,0,0] neg_hi:[1,0,0]
	ds_read_b128 v[110:113], v10 offset:11520
	ds_read_b128 v[106:109], v10 offset:11264
	ds_read_b128 v[118:121], v10 offset:12032
	ds_read_b128 v[114:117], v10 offset:11776
	ds_read_b128 v[70:73], v11 offset:768
	s_waitcnt lgkmcnt(5)
	v_fma_mix_f32 v12, v6, v88, v180 op_sel_hi:[0,1,0]
	v_fma_mix_f32 v12, v7, v88, v12 op_sel:[0,1,0] op_sel_hi:[0,1,0]
	v_fma_mix_f32 v12, v8, v89, v12 op_sel_hi:[0,1,0]
	v_fma_mix_f32 v12, v9, v89, v12 op_sel:[0,1,0] op_sel_hi:[0,1,0]
	v_pk_mul_f32 v[48:49], v[6:7], v[84:85]
	v_pk_mul_f32 v[50:51], v[8:9], v[86:87]
	v_add_f32_dpp v12, v12, v12 row_ror:1 row_mask:0xf bank_mask:0xf bound_ctrl:1
	v_fma_mix_f32 v100, v6, v38, v180 op_sel_hi:[0,1,0]
	v_fma_mix_f32 v100, v7, v38, v100 op_sel:[0,1,0] op_sel_hi:[0,1,0]
	v_add_f32_dpp v12, v12, v12 row_ror:2 row_mask:0xf bank_mask:0xf bound_ctrl:1
	v_pk_fma_f32 v[48:49], v[96:97], v[68:69], v[48:49] op_sel_hi:[1,0,1]
	v_pk_fma_f32 v[50:51], v[98:99], v[68:69], v[50:51] op_sel_hi:[1,0,1]
	v_add_f32_dpp v12, v12, v12 row_ror:4 row_mask:0xf bank_mask:0xf bound_ctrl:1
	v_fma_mix_f32 v100, v8, v39, v100 op_sel_hi:[0,1,0]
	v_fma_mix_f32 v100, v9, v39, v100 op_sel:[0,1,0] op_sel_hi:[0,1,0]
	v_add_f32_dpp v12, v12, v12 row_ror:8 row_mask:0xf bank_mask:0xf bound_ctrl:1
	v_pk_fma_f32 v[6:7], v[92:93], v[12:13], v[48:49] op_sel_hi:[1,0,1] neg_lo:[1,0,0] neg_hi:[1,0,0]
	v_pk_fma_f32 v[8:9], v[94:95], v[12:13], v[50:51] op_sel_hi:[1,0,1] neg_lo:[1,0,0] neg_hi:[1,0,0]
	ds_read_b128 v[20:23], v10 offset:12544
	ds_read_b128 v[16:19], v10 offset:12288
	ds_read_b128 v[28:31], v10 offset:13056
	ds_read_b128 v[24:27], v10 offset:12800
	s_waitcnt lgkmcnt(5)
	v_fma_mix_f32 v12, v6, v110, v180 op_sel_hi:[0,1,0]
	v_fma_mix_f32 v12, v7, v110, v12 op_sel:[0,1,0] op_sel_hi:[0,1,0]
	v_fma_mix_f32 v12, v8, v111, v12 op_sel_hi:[0,1,0]
	v_fma_mix_f32 v12, v9, v111, v12 op_sel:[0,1,0] op_sel_hi:[0,1,0]
	v_pk_mul_f32 v[48:49], v[6:7], v[106:107]
	v_pk_mul_f32 v[50:51], v[8:9], v[108:109]
	v_add_f32_dpp v12, v12, v12 row_ror:1 row_mask:0xf bank_mask:0xf bound_ctrl:1
	v_fma_mix_f32 v101, v6, v90, v180 op_sel_hi:[0,1,0]
	v_fma_mix_f32 v101, v7, v90, v101 op_sel:[0,1,0] op_sel_hi:[0,1,0]
	v_add_f32_dpp v12, v12, v12 row_ror:2 row_mask:0xf bank_mask:0xf bound_ctrl:1
	v_pk_fma_f32 v[48:49], v[118:119], v[68:69], v[48:49] op_sel:[0,1,0]
	v_pk_fma_f32 v[50:51], v[120:121], v[68:69], v[50:51] op_sel:[0,1,0]
	v_add_f32_dpp v12, v12, v12 row_ror:4 row_mask:0xf bank_mask:0xf bound_ctrl:1
	v_fma_mix_f32 v101, v8, v91, v101 op_sel_hi:[0,1,0]
	v_fma_mix_f32 v101, v9, v91, v101 op_sel:[0,1,0] op_sel_hi:[0,1,0]
	v_add_f32_dpp v12, v12, v12 row_ror:8 row_mask:0xf bank_mask:0xf bound_ctrl:1
	v_pk_fma_f32 v[6:7], v[114:115], v[12:13], v[48:49] op_sel_hi:[1,0,1] neg_lo:[1,0,0] neg_hi:[1,0,0]
	v_pk_fma_f32 v[8:9], v[116:117], v[12:13], v[50:51] op_sel_hi:[1,0,1] neg_lo:[1,0,0] neg_hi:[1,0,0]
	ds_read_b128 v[36:39], v10 offset:13568
	ds_read_b128 v[32:35], v10 offset:13312
	ds_read_b128 v[44:47], v10 offset:14080
	ds_read_b128 v[40:43], v10 offset:13824
	s_waitcnt lgkmcnt(4)
	v_fma_mix_f32 v12, v6, v20, v180 op_sel_hi:[0,1,0]
	v_fma_mix_f32 v12, v7, v20, v12 op_sel:[0,1,0] op_sel_hi:[0,1,0]
	v_fma_mix_f32 v12, v8, v21, v12 op_sel_hi:[0,1,0]
	v_fma_mix_f32 v12, v9, v21, v12 op_sel:[0,1,0] op_sel_hi:[0,1,0]
	v_pk_mul_f32 v[48:49], v[6:7], v[16:17]
	v_pk_mul_f32 v[50:51], v[8:9], v[18:19]
	v_add_f32_dpp v12, v12, v12 row_ror:1 row_mask:0xf bank_mask:0xf bound_ctrl:1
	v_fma_mix_f32 v102, v6, v112, v180 op_sel_hi:[0,1,0]
	v_fma_mix_f32 v102, v7, v112, v102 op_sel:[0,1,0] op_sel_hi:[0,1,0]
	v_add_f32_dpp v12, v12, v12 row_ror:2 row_mask:0xf bank_mask:0xf bound_ctrl:1
	v_pk_fma_f32 v[48:49], v[28:29], v[70:71], v[48:49] op_sel_hi:[1,0,1]
	v_pk_fma_f32 v[50:51], v[30:31], v[70:71], v[50:51] op_sel_hi:[1,0,1]
	v_add_f32_dpp v12, v12, v12 row_ror:4 row_mask:0xf bank_mask:0xf bound_ctrl:1
	v_fma_mix_f32 v102, v8, v113, v102 op_sel_hi:[0,1,0]
	v_fma_mix_f32 v102, v9, v113, v102 op_sel:[0,1,0] op_sel_hi:[0,1,0]
	v_add_f32_dpp v12, v12, v12 row_ror:8 row_mask:0xf bank_mask:0xf bound_ctrl:1
	v_pk_fma_f32 v[6:7], v[24:25], v[12:13], v[48:49] op_sel_hi:[1,0,1] neg_lo:[1,0,0] neg_hi:[1,0,0]
	v_pk_fma_f32 v[8:9], v[26:27], v[12:13], v[50:51] op_sel_hi:[1,0,1] neg_lo:[1,0,0] neg_hi:[1,0,0]
	ds_read_b128 v[88:91], v10 offset:14592
	ds_read_b128 v[84:87], v10 offset:14336
	ds_read_b128 v[96:99], v10 offset:15104
	ds_read_b128 v[92:95], v10 offset:14848
	s_waitcnt lgkmcnt(4)
	v_fma_mix_f32 v12, v6, v36, v180 op_sel_hi:[0,1,0]
	v_fma_mix_f32 v12, v7, v36, v12 op_sel:[0,1,0] op_sel_hi:[0,1,0]
	v_fma_mix_f32 v12, v8, v37, v12 op_sel_hi:[0,1,0]
	v_fma_mix_f32 v12, v9, v37, v12 op_sel:[0,1,0] op_sel_hi:[0,1,0]
	v_pk_mul_f32 v[48:49], v[6:7], v[32:33]
	v_pk_mul_f32 v[50:51], v[8:9], v[34:35]
	v_add_f32_dpp v12, v12, v12 row_ror:1 row_mask:0xf bank_mask:0xf bound_ctrl:1
	v_fma_mix_f32 v103, v6, v22, v180 op_sel_hi:[0,1,0]
	v_fma_mix_f32 v103, v7, v22, v103 op_sel:[0,1,0] op_sel_hi:[0,1,0]
	v_add_f32_dpp v12, v12, v12 row_ror:2 row_mask:0xf bank_mask:0xf bound_ctrl:1
	v_pk_fma_f32 v[48:49], v[44:45], v[70:71], v[48:49] op_sel:[0,1,0]
	v_pk_fma_f32 v[50:51], v[46:47], v[70:71], v[50:51] op_sel:[0,1,0]
	v_add_f32_dpp v12, v12, v12 row_ror:4 row_mask:0xf bank_mask:0xf bound_ctrl:1
	v_fma_mix_f32 v103, v8, v23, v103 op_sel_hi:[0,1,0]
	v_fma_mix_f32 v103, v9, v23, v103 op_sel:[0,1,0] op_sel_hi:[0,1,0]
	v_add_f32_dpp v12, v12, v12 row_ror:8 row_mask:0xf bank_mask:0xf bound_ctrl:1
	v_pk_fma_f32 v[6:7], v[40:41], v[12:13], v[48:49] op_sel_hi:[1,0,1] neg_lo:[1,0,0] neg_hi:[1,0,0]
	v_pk_fma_f32 v[8:9], v[42:43], v[12:13], v[50:51] op_sel_hi:[1,0,1] neg_lo:[1,0,0] neg_hi:[1,0,0]
	ds_read_b128 v[110:113], v10 offset:15616
	ds_read_b128 v[106:109], v10 offset:15360
	ds_read_b128 v[118:121], v10 offset:16128
	ds_read_b128 v[114:117], v10 offset:15872
	ds_read_b128 v[66:69], v11 offset:1024
	s_waitcnt lgkmcnt(5)
	v_fma_mix_f32 v12, v6, v88, v180 op_sel_hi:[0,1,0]
	v_fma_mix_f32 v12, v7, v88, v12 op_sel:[0,1,0] op_sel_hi:[0,1,0]
	v_fma_mix_f32 v12, v8, v89, v12 op_sel_hi:[0,1,0]
	v_fma_mix_f32 v12, v9, v89, v12 op_sel:[0,1,0] op_sel_hi:[0,1,0]
	v_pk_mul_f32 v[48:49], v[6:7], v[84:85]
	v_pk_mul_f32 v[50:51], v[8:9], v[86:87]
	v_add_f32_dpp v12, v12, v12 row_ror:1 row_mask:0xf bank_mask:0xf bound_ctrl:1
	v_fma_mix_f32 v104, v6, v38, v180 op_sel_hi:[0,1,0]
	v_fma_mix_f32 v104, v7, v38, v104 op_sel:[0,1,0] op_sel_hi:[0,1,0]
	v_add_f32_dpp v12, v12, v12 row_ror:2 row_mask:0xf bank_mask:0xf bound_ctrl:1
	v_pk_fma_f32 v[48:49], v[96:97], v[72:73], v[48:49] op_sel_hi:[1,0,1]
	v_pk_fma_f32 v[50:51], v[98:99], v[72:73], v[50:51] op_sel_hi:[1,0,1]
	v_add_f32_dpp v12, v12, v12 row_ror:4 row_mask:0xf bank_mask:0xf bound_ctrl:1
	v_fma_mix_f32 v104, v8, v39, v104 op_sel_hi:[0,1,0]
	v_fma_mix_f32 v104, v9, v39, v104 op_sel:[0,1,0] op_sel_hi:[0,1,0]
	v_add_f32_dpp v12, v12, v12 row_ror:8 row_mask:0xf bank_mask:0xf bound_ctrl:1
	v_pk_fma_f32 v[6:7], v[92:93], v[12:13], v[48:49] op_sel_hi:[1,0,1] neg_lo:[1,0,0] neg_hi:[1,0,0]
	v_pk_fma_f32 v[8:9], v[94:95], v[12:13], v[50:51] op_sel_hi:[1,0,1] neg_lo:[1,0,0] neg_hi:[1,0,0]
	ds_read_b128 v[20:23], v10 offset:16640
	ds_read_b128 v[16:19], v10 offset:16384
	ds_read_b128 v[28:31], v10 offset:17152
	ds_read_b128 v[24:27], v10 offset:16896
	s_waitcnt lgkmcnt(5)
	v_fma_mix_f32 v12, v6, v110, v180 op_sel_hi:[0,1,0]
	v_fma_mix_f32 v12, v7, v110, v12 op_sel:[0,1,0] op_sel_hi:[0,1,0]
	v_fma_mix_f32 v12, v8, v111, v12 op_sel_hi:[0,1,0]
	v_fma_mix_f32 v12, v9, v111, v12 op_sel:[0,1,0] op_sel_hi:[0,1,0]
	v_pk_mul_f32 v[48:49], v[6:7], v[106:107]
	v_pk_mul_f32 v[50:51], v[8:9], v[108:109]
	v_add_f32_dpp v12, v12, v12 row_ror:1 row_mask:0xf bank_mask:0xf bound_ctrl:1
	v_fma_mix_f32 v105, v6, v90, v180 op_sel_hi:[0,1,0]
	v_fma_mix_f32 v105, v7, v90, v105 op_sel:[0,1,0] op_sel_hi:[0,1,0]
	v_add_f32_dpp v12, v12, v12 row_ror:2 row_mask:0xf bank_mask:0xf bound_ctrl:1
	v_pk_fma_f32 v[48:49], v[118:119], v[72:73], v[48:49] op_sel:[0,1,0]
	v_pk_fma_f32 v[50:51], v[120:121], v[72:73], v[50:51] op_sel:[0,1,0]
	v_add_f32_dpp v12, v12, v12 row_ror:4 row_mask:0xf bank_mask:0xf bound_ctrl:1
	v_fma_mix_f32 v105, v8, v91, v105 op_sel_hi:[0,1,0]
	v_fma_mix_f32 v105, v9, v91, v105 op_sel:[0,1,0] op_sel_hi:[0,1,0]
	v_add_f32_dpp v12, v12, v12 row_ror:8 row_mask:0xf bank_mask:0xf bound_ctrl:1
	v_pk_fma_f32 v[6:7], v[114:115], v[12:13], v[48:49] op_sel_hi:[1,0,1] neg_lo:[1,0,0] neg_hi:[1,0,0]
	v_pk_fma_f32 v[8:9], v[116:117], v[12:13], v[50:51] op_sel_hi:[1,0,1] neg_lo:[1,0,0] neg_hi:[1,0,0]
	ds_read_b128 v[36:39], v10 offset:17664
	ds_read_b128 v[32:35], v10 offset:17408
	ds_read_b128 v[44:47], v10 offset:18176
	ds_read_b128 v[40:43], v10 offset:17920
	s_waitcnt lgkmcnt(4)
	v_fma_mix_f32 v12, v6, v20, v180 op_sel_hi:[0,1,0]
	v_fma_mix_f32 v12, v7, v20, v12 op_sel:[0,1,0] op_sel_hi:[0,1,0]
	v_fma_mix_f32 v12, v8, v21, v12 op_sel_hi:[0,1,0]
	v_fma_mix_f32 v12, v9, v21, v12 op_sel:[0,1,0] op_sel_hi:[0,1,0]
	v_pk_mul_f32 v[48:49], v[6:7], v[16:17]
	v_pk_mul_f32 v[50:51], v[8:9], v[18:19]
	v_add_f32_dpp v12, v12, v12 row_ror:1 row_mask:0xf bank_mask:0xf bound_ctrl:1
	v_fma_mix_f32 v61, v6, v112, v180 op_sel_hi:[0,1,0]
	v_fma_mix_f32 v61, v7, v112, v61 op_sel:[0,1,0] op_sel_hi:[0,1,0]
	v_add_f32_dpp v12, v12, v12 row_ror:2 row_mask:0xf bank_mask:0xf bound_ctrl:1
	v_pk_fma_f32 v[48:49], v[28:29], v[66:67], v[48:49] op_sel_hi:[1,0,1]
	v_pk_fma_f32 v[50:51], v[30:31], v[66:67], v[50:51] op_sel_hi:[1,0,1]
	v_add_f32_dpp v12, v12, v12 row_ror:4 row_mask:0xf bank_mask:0xf bound_ctrl:1
	v_fma_mix_f32 v61, v8, v113, v61 op_sel_hi:[0,1,0]
	v_fma_mix_f32 v61, v9, v113, v61 op_sel:[0,1,0] op_sel_hi:[0,1,0]
	v_add_f32_dpp v12, v12, v12 row_ror:8 row_mask:0xf bank_mask:0xf bound_ctrl:1
	v_pk_fma_f32 v[6:7], v[24:25], v[12:13], v[48:49] op_sel_hi:[1,0,1] neg_lo:[1,0,0] neg_hi:[1,0,0]
	v_pk_fma_f32 v[8:9], v[26:27], v[12:13], v[50:51] op_sel_hi:[1,0,1] neg_lo:[1,0,0] neg_hi:[1,0,0]
	ds_read_b128 v[88:91], v10 offset:18688
	ds_read_b128 v[84:87], v10 offset:18432
	ds_read_b128 v[96:99], v10 offset:19200
	ds_read_b128 v[92:95], v10 offset:18944
	v_add_f32_dpp v83, v83, v83 row_ror:8 row_mask:0xf bank_mask:0xc
	v_add_f32_dpp v83, v52, v52 row_ror:8 row_mask:0xf bank_mask:0x3
	v_add_f32_dpp v100, v100, v100 row_ror:8 row_mask:0xf bank_mask:0xc
	v_add_f32_dpp v100, v53, v53 row_ror:8 row_mask:0xf bank_mask:0x3
	v_add_f32_dpp v101, v101, v101 row_ror:8 row_mask:0xf bank_mask:0xc
	v_add_f32_dpp v101, v54, v54 row_ror:8 row_mask:0xf bank_mask:0x3
	v_add_f32_dpp v102, v102, v102 row_ror:8 row_mask:0xf bank_mask:0xc
	v_add_f32_dpp v102, v55, v55 row_ror:8 row_mask:0xf bank_mask:0x3
	v_add_f32_dpp v103, v103, v103 row_ror:8 row_mask:0xf bank_mask:0xc
	v_add_f32_dpp v103, v56, v56 row_ror:8 row_mask:0xf bank_mask:0x3
	v_add_f32_dpp v104, v104, v104 row_ror:8 row_mask:0xf bank_mask:0xc
	v_add_f32_dpp v104, v57, v57 row_ror:8 row_mask:0xf bank_mask:0x3
	v_add_f32_dpp v105, v105, v105 row_ror:8 row_mask:0xf bank_mask:0xc
	v_add_f32_dpp v105, v81, v81 row_ror:8 row_mask:0xf bank_mask:0x3
	v_add_f32_dpp v61, v61, v61 row_ror:8 row_mask:0xf bank_mask:0xc
	v_add_f32_dpp v61, v82, v82 row_ror:8 row_mask:0xf bank_mask:0x3
	v_add_f32_dpp v103, v103, v103 row_ror:4 row_mask:0xf bank_mask:0xa
	v_add_f32_dpp v103, v83, v83 row_ror:12 row_mask:0xf bank_mask:0x5
	v_add_f32_dpp v104, v104, v104 row_ror:4 row_mask:0xf bank_mask:0xa
	v_add_f32_dpp v104, v100, v100 row_ror:12 row_mask:0xf bank_mask:0x5
	v_add_f32_dpp v105, v105, v105 row_ror:4 row_mask:0xf bank_mask:0xa
	v_add_f32_dpp v105, v101, v101 row_ror:12 row_mask:0xf bank_mask:0x5
	v_add_f32_dpp v61, v61, v61 row_ror:4 row_mask:0xf bank_mask:0xa
	v_add_f32_dpp v61, v102, v102 row_ror:12 row_mask:0xf bank_mask:0x5
	v_cndmask_b32_e64 v62, v105, v103, s[38:39]
	v_cndmask_b32_e64 v63, v103, v105, s[38:39]
	v_cndmask_b32_e64 v64, v61, v104, s[38:39]
	v_cndmask_b32_e64 v65, v104, v61, s[38:39]
	v_add_f32_dpp v62, v63, v62 quad_perm:[2,3,0,1] row_mask:0xf bank_mask:0xf bound_ctrl:1
	s_nop 0
	v_add_f32_dpp v63, v65, v64 quad_perm:[2,3,0,1] row_mask:0xf bank_mask:0xf bound_ctrl:1
	v_cndmask_b32_e64 v65, v63, v62, s[40:41]
	v_cndmask_b32_e64 v62, v62, v63, s[40:41]
	s_nop 1
	v_add_f32_dpp v62, v62, v65 quad_perm:[1,0,3,2] row_mask:0xf bank_mask:0xf bound_ctrl:1
	v_cvt_pk_bf16_f32 v62, v62, v62
	global_store_short v[2:3], v62, off
	v_lshl_add_u64 v[2:3], v[2:3], 0, s[84:85]
	s_waitcnt lgkmcnt(4)
	v_fma_mix_f32 v12, v6, v36, v180 op_sel_hi:[0,1,0]
	v_fma_mix_f32 v12, v7, v36, v12 op_sel:[0,1,0] op_sel_hi:[0,1,0]
	v_fma_mix_f32 v12, v8, v37, v12 op_sel_hi:[0,1,0]
	v_fma_mix_f32 v12, v9, v37, v12 op_sel:[0,1,0] op_sel_hi:[0,1,0]
	v_pk_mul_f32 v[48:49], v[6:7], v[32:33]
	v_pk_mul_f32 v[50:51], v[8:9], v[34:35]
	v_add_f32_dpp v12, v12, v12 row_ror:1 row_mask:0xf bank_mask:0xf bound_ctrl:1
	v_fma_mix_f32 v52, v6, v22, v180 op_sel_hi:[0,1,0]
	v_fma_mix_f32 v52, v7, v22, v52 op_sel:[0,1,0] op_sel_hi:[0,1,0]
	v_add_f32_dpp v12, v12, v12 row_ror:2 row_mask:0xf bank_mask:0xf bound_ctrl:1
	v_pk_fma_f32 v[48:49], v[44:45], v[66:67], v[48:49] op_sel:[0,1,0]
	v_pk_fma_f32 v[50:51], v[46:47], v[66:67], v[50:51] op_sel:[0,1,0]
	v_add_f32_dpp v12, v12, v12 row_ror:4 row_mask:0xf bank_mask:0xf bound_ctrl:1
	v_fma_mix_f32 v52, v8, v23, v52 op_sel_hi:[0,1,0]
	v_fma_mix_f32 v52, v9, v23, v52 op_sel:[0,1,0] op_sel_hi:[0,1,0]
	v_add_f32_dpp v12, v12, v12 row_ror:8 row_mask:0xf bank_mask:0xf bound_ctrl:1
	v_pk_fma_f32 v[6:7], v[40:41], v[12:13], v[48:49] op_sel_hi:[1,0,1] neg_lo:[1,0,0] neg_hi:[1,0,0]
	v_pk_fma_f32 v[8:9], v[42:43], v[12:13], v[50:51] op_sel_hi:[1,0,1] neg_lo:[1,0,0] neg_hi:[1,0,0]
	ds_read_b128 v[110:113], v10 offset:19712
	ds_read_b128 v[106:109], v10 offset:19456
	ds_read_b128 v[118:121], v10 offset:20224
	ds_read_b128 v[114:117], v10 offset:19968
	ds_read_b128 v[70:73], v11 offset:1280
	s_waitcnt lgkmcnt(5)
	v_fma_mix_f32 v12, v6, v88, v180 op_sel_hi:[0,1,0]
	v_fma_mix_f32 v12, v7, v88, v12 op_sel:[0,1,0] op_sel_hi:[0,1,0]
	v_fma_mix_f32 v12, v8, v89, v12 op_sel_hi:[0,1,0]
	v_fma_mix_f32 v12, v9, v89, v12 op_sel:[0,1,0] op_sel_hi:[0,1,0]
	v_pk_mul_f32 v[48:49], v[6:7], v[84:85]
	v_pk_mul_f32 v[50:51], v[8:9], v[86:87]
	v_add_f32_dpp v12, v12, v12 row_ror:1 row_mask:0xf bank_mask:0xf bound_ctrl:1
	v_fma_mix_f32 v53, v6, v38, v180 op_sel_hi:[0,1,0]
	v_fma_mix_f32 v53, v7, v38, v53 op_sel:[0,1,0] op_sel_hi:[0,1,0]
	v_add_f32_dpp v12, v12, v12 row_ror:2 row_mask:0xf bank_mask:0xf bound_ctrl:1
	v_pk_fma_f32 v[48:49], v[96:97], v[68:69], v[48:49] op_sel_hi:[1,0,1]
	v_pk_fma_f32 v[50:51], v[98:99], v[68:69], v[50:51] op_sel_hi:[1,0,1]
	v_add_f32_dpp v12, v12, v12 row_ror:4 row_mask:0xf bank_mask:0xf bound_ctrl:1
	v_fma_mix_f32 v53, v8, v39, v53 op_sel_hi:[0,1,0]
	v_fma_mix_f32 v53, v9, v39, v53 op_sel:[0,1,0] op_sel_hi:[0,1,0]
	v_add_f32_dpp v12, v12, v12 row_ror:8 row_mask:0xf bank_mask:0xf bound_ctrl:1
	v_pk_fma_f32 v[6:7], v[92:93], v[12:13], v[48:49] op_sel_hi:[1,0,1] neg_lo:[1,0,0] neg_hi:[1,0,0]
	v_pk_fma_f32 v[8:9], v[94:95], v[12:13], v[50:51] op_sel_hi:[1,0,1] neg_lo:[1,0,0] neg_hi:[1,0,0]
	ds_read_b128 v[20:23], v10 offset:20736
	ds_read_b128 v[16:19], v10 offset:20480
	ds_read_b128 v[28:31], v10 offset:21248
	ds_read_b128 v[24:27], v10 offset:20992
	s_waitcnt lgkmcnt(5)
	v_fma_mix_f32 v12, v6, v110, v180 op_sel_hi:[0,1,0]
	v_fma_mix_f32 v12, v7, v110, v12 op_sel:[0,1,0] op_sel_hi:[0,1,0]
	v_fma_mix_f32 v12, v8, v111, v12 op_sel_hi:[0,1,0]
	v_fma_mix_f32 v12, v9, v111, v12 op_sel:[0,1,0] op_sel_hi:[0,1,0]
	v_pk_mul_f32 v[48:49], v[6:7], v[106:107]
	v_pk_mul_f32 v[50:51], v[8:9], v[108:109]
	v_add_f32_dpp v12, v12, v12 row_ror:1 row_mask:0xf bank_mask:0xf bound_ctrl:1
	v_fma_mix_f32 v54, v6, v90, v180 op_sel_hi:[0,1,0]
	v_fma_mix_f32 v54, v7, v90, v54 op_sel:[0,1,0] op_sel_hi:[0,1,0]
	v_add_f32_dpp v12, v12, v12 row_ror:2 row_mask:0xf bank_mask:0xf bound_ctrl:1
	v_pk_fma_f32 v[48:49], v[118:119], v[68:69], v[48:49] op_sel:[0,1,0]
	v_pk_fma_f32 v[50:51], v[120:121], v[68:69], v[50:51] op_sel:[0,1,0]
	v_add_f32_dpp v12, v12, v12 row_ror:4 row_mask:0xf bank_mask:0xf bound_ctrl:1
	v_fma_mix_f32 v54, v8, v91, v54 op_sel_hi:[0,1,0]
	v_fma_mix_f32 v54, v9, v91, v54 op_sel:[0,1,0] op_sel_hi:[0,1,0]
	v_add_f32_dpp v12, v12, v12 row_ror:8 row_mask:0xf bank_mask:0xf bound_ctrl:1
	v_pk_fma_f32 v[6:7], v[114:115], v[12:13], v[48:49] op_sel_hi:[1,0,1] neg_lo:[1,0,0] neg_hi:[1,0,0]
	v_pk_fma_f32 v[8:9], v[116:117], v[12:13], v[50:51] op_sel_hi:[1,0,1] neg_lo:[1,0,0] neg_hi:[1,0,0]
	ds_read_b128 v[36:39], v10 offset:21760
	ds_read_b128 v[32:35], v10 offset:21504
	ds_read_b128 v[44:47], v10 offset:22272
	ds_read_b128 v[40:43], v10 offset:22016
	s_waitcnt lgkmcnt(4)
	v_fma_mix_f32 v12, v6, v20, v180 op_sel_hi:[0,1,0]
	v_fma_mix_f32 v12, v7, v20, v12 op_sel:[0,1,0] op_sel_hi:[0,1,0]
	v_fma_mix_f32 v12, v8, v21, v12 op_sel_hi:[0,1,0]
	v_fma_mix_f32 v12, v9, v21, v12 op_sel:[0,1,0] op_sel_hi:[0,1,0]
	v_pk_mul_f32 v[48:49], v[6:7], v[16:17]
	v_pk_mul_f32 v[50:51], v[8:9], v[18:19]
	v_add_f32_dpp v12, v12, v12 row_ror:1 row_mask:0xf bank_mask:0xf bound_ctrl:1
	v_fma_mix_f32 v55, v6, v112, v180 op_sel_hi:[0,1,0]
	v_fma_mix_f32 v55, v7, v112, v55 op_sel:[0,1,0] op_sel_hi:[0,1,0]
	v_add_f32_dpp v12, v12, v12 row_ror:2 row_mask:0xf bank_mask:0xf bound_ctrl:1
	v_pk_fma_f32 v[48:49], v[28:29], v[70:71], v[48:49] op_sel_hi:[1,0,1]
	v_pk_fma_f32 v[50:51], v[30:31], v[70:71], v[50:51] op_sel_hi:[1,0,1]
	v_add_f32_dpp v12, v12, v12 row_ror:4 row_mask:0xf bank_mask:0xf bound_ctrl:1
	v_fma_mix_f32 v55, v8, v113, v55 op_sel_hi:[0,1,0]
	v_fma_mix_f32 v55, v9, v113, v55 op_sel:[0,1,0] op_sel_hi:[0,1,0]
	v_add_f32_dpp v12, v12, v12 row_ror:8 row_mask:0xf bank_mask:0xf bound_ctrl:1
	v_pk_fma_f32 v[6:7], v[24:25], v[12:13], v[48:49] op_sel_hi:[1,0,1] neg_lo:[1,0,0] neg_hi:[1,0,0]
	v_pk_fma_f32 v[8:9], v[26:27], v[12:13], v[50:51] op_sel_hi:[1,0,1] neg_lo:[1,0,0] neg_hi:[1,0,0]
	ds_read_b128 v[88:91], v10 offset:22784
	ds_read_b128 v[84:87], v10 offset:22528
	ds_read_b128 v[96:99], v10 offset:23296
	ds_read_b128 v[92:95], v10 offset:23040
	s_waitcnt lgkmcnt(4)
	v_fma_mix_f32 v12, v6, v36, v180 op_sel_hi:[0,1,0]
	v_fma_mix_f32 v12, v7, v36, v12 op_sel:[0,1,0] op_sel_hi:[0,1,0]
	v_fma_mix_f32 v12, v8, v37, v12 op_sel_hi:[0,1,0]
	v_fma_mix_f32 v12, v9, v37, v12 op_sel:[0,1,0] op_sel_hi:[0,1,0]
	v_pk_mul_f32 v[48:49], v[6:7], v[32:33]
	v_pk_mul_f32 v[50:51], v[8:9], v[34:35]
	v_add_f32_dpp v12, v12, v12 row_ror:1 row_mask:0xf bank_mask:0xf bound_ctrl:1
	v_fma_mix_f32 v56, v6, v22, v180 op_sel_hi:[0,1,0]
	v_fma_mix_f32 v56, v7, v22, v56 op_sel:[0,1,0] op_sel_hi:[0,1,0]
	v_add_f32_dpp v12, v12, v12 row_ror:2 row_mask:0xf bank_mask:0xf bound_ctrl:1
	v_pk_fma_f32 v[48:49], v[44:45], v[70:71], v[48:49] op_sel:[0,1,0]
	v_pk_fma_f32 v[50:51], v[46:47], v[70:71], v[50:51] op_sel:[0,1,0]
	v_add_f32_dpp v12, v12, v12 row_ror:4 row_mask:0xf bank_mask:0xf bound_ctrl:1
	v_fma_mix_f32 v56, v8, v23, v56 op_sel_hi:[0,1,0]
	v_fma_mix_f32 v56, v9, v23, v56 op_sel:[0,1,0] op_sel_hi:[0,1,0]
	v_add_f32_dpp v12, v12, v12 row_ror:8 row_mask:0xf bank_mask:0xf bound_ctrl:1
	v_pk_fma_f32 v[6:7], v[40:41], v[12:13], v[48:49] op_sel_hi:[1,0,1] neg_lo:[1,0,0] neg_hi:[1,0,0]
	v_pk_fma_f32 v[8:9], v[42:43], v[12:13], v[50:51] op_sel_hi:[1,0,1] neg_lo:[1,0,0] neg_hi:[1,0,0]
	ds_read_b128 v[110:113], v10 offset:23808
	ds_read_b128 v[106:109], v10 offset:23552
	ds_read_b128 v[118:121], v10 offset:24320
	ds_read_b128 v[114:117], v10 offset:24064
	ds_read_b128 v[66:69], v11 offset:1536
	s_waitcnt lgkmcnt(5)
	v_fma_mix_f32 v12, v6, v88, v180 op_sel_hi:[0,1,0]
	v_fma_mix_f32 v12, v7, v88, v12 op_sel:[0,1,0] op_sel_hi:[0,1,0]
	v_fma_mix_f32 v12, v8, v89, v12 op_sel_hi:[0,1,0]
	v_fma_mix_f32 v12, v9, v89, v12 op_sel:[0,1,0] op_sel_hi:[0,1,0]
	v_pk_mul_f32 v[48:49], v[6:7], v[84:85]
	v_pk_mul_f32 v[50:51], v[8:9], v[86:87]
	v_add_f32_dpp v12, v12, v12 row_ror:1 row_mask:0xf bank_mask:0xf bound_ctrl:1
	v_fma_mix_f32 v57, v6, v38, v180 op_sel_hi:[0,1,0]
	v_fma_mix_f32 v57, v7, v38, v57 op_sel:[0,1,0] op_sel_hi:[0,1,0]
	v_add_f32_dpp v12, v12, v12 row_ror:2 row_mask:0xf bank_mask:0xf bound_ctrl:1
	v_pk_fma_f32 v[48:49], v[96:97], v[72:73], v[48:49] op_sel_hi:[1,0,1]
	v_pk_fma_f32 v[50:51], v[98:99], v[72:73], v[50:51] op_sel_hi:[1,0,1]
	v_add_f32_dpp v12, v12, v12 row_ror:4 row_mask:0xf bank_mask:0xf bound_ctrl:1
	v_fma_mix_f32 v57, v8, v39, v57 op_sel_hi:[0,1,0]
	v_fma_mix_f32 v57, v9, v39, v57 op_sel:[0,1,0] op_sel_hi:[0,1,0]
	v_add_f32_dpp v12, v12, v12 row_ror:8 row_mask:0xf bank_mask:0xf bound_ctrl:1
	v_pk_fma_f32 v[6:7], v[92:93], v[12:13], v[48:49] op_sel_hi:[1,0,1] neg_lo:[1,0,0] neg_hi:[1,0,0]
	v_pk_fma_f32 v[8:9], v[94:95], v[12:13], v[50:51] op_sel_hi:[1,0,1] neg_lo:[1,0,0] neg_hi:[1,0,0]
	ds_read_b128 v[20:23], v10 offset:24832
	ds_read_b128 v[16:19], v10 offset:24576
	ds_read_b128 v[28:31], v10 offset:25344
	ds_read_b128 v[24:27], v10 offset:25088
	s_waitcnt lgkmcnt(5)
	v_fma_mix_f32 v12, v6, v110, v180 op_sel_hi:[0,1,0]
	v_fma_mix_f32 v12, v7, v110, v12 op_sel:[0,1,0] op_sel_hi:[0,1,0]
	v_fma_mix_f32 v12, v8, v111, v12 op_sel_hi:[0,1,0]
	v_fma_mix_f32 v12, v9, v111, v12 op_sel:[0,1,0] op_sel_hi:[0,1,0]
	v_pk_mul_f32 v[48:49], v[6:7], v[106:107]
	v_pk_mul_f32 v[50:51], v[8:9], v[108:109]
	v_add_f32_dpp v12, v12, v12 row_ror:1 row_mask:0xf bank_mask:0xf bound_ctrl:1
	v_fma_mix_f32 v81, v6, v90, v180 op_sel_hi:[0,1,0]
	v_fma_mix_f32 v81, v7, v90, v81 op_sel:[0,1,0] op_sel_hi:[0,1,0]
	v_add_f32_dpp v12, v12, v12 row_ror:2 row_mask:0xf bank_mask:0xf bound_ctrl:1
	v_pk_fma_f32 v[48:49], v[118:119], v[72:73], v[48:49] op_sel:[0,1,0]
	v_pk_fma_f32 v[50:51], v[120:121], v[72:73], v[50:51] op_sel:[0,1,0]
	v_add_f32_dpp v12, v12, v12 row_ror:4 row_mask:0xf bank_mask:0xf bound_ctrl:1
	v_fma_mix_f32 v81, v8, v91, v81 op_sel_hi:[0,1,0]
	v_fma_mix_f32 v81, v9, v91, v81 op_sel:[0,1,0] op_sel_hi:[0,1,0]
	v_add_f32_dpp v12, v12, v12 row_ror:8 row_mask:0xf bank_mask:0xf bound_ctrl:1
	v_pk_fma_f32 v[6:7], v[114:115], v[12:13], v[48:49] op_sel_hi:[1,0,1] neg_lo:[1,0,0] neg_hi:[1,0,0]
	v_pk_fma_f32 v[8:9], v[116:117], v[12:13], v[50:51] op_sel_hi:[1,0,1] neg_lo:[1,0,0] neg_hi:[1,0,0]
	ds_read_b128 v[36:39], v10 offset:25856
	ds_read_b128 v[32:35], v10 offset:25600
	ds_read_b128 v[44:47], v10 offset:26368
	ds_read_b128 v[40:43], v10 offset:26112
	s_waitcnt lgkmcnt(4)
	v_fma_mix_f32 v12, v6, v20, v180 op_sel_hi:[0,1,0]
	v_fma_mix_f32 v12, v7, v20, v12 op_sel:[0,1,0] op_sel_hi:[0,1,0]
	v_fma_mix_f32 v12, v8, v21, v12 op_sel_hi:[0,1,0]
	v_fma_mix_f32 v12, v9, v21, v12 op_sel:[0,1,0] op_sel_hi:[0,1,0]
	v_pk_mul_f32 v[48:49], v[6:7], v[16:17]
	v_pk_mul_f32 v[50:51], v[8:9], v[18:19]
	v_add_f32_dpp v12, v12, v12 row_ror:1 row_mask:0xf bank_mask:0xf bound_ctrl:1
	v_fma_mix_f32 v82, v6, v112, v180 op_sel_hi:[0,1,0]
	v_fma_mix_f32 v82, v7, v112, v82 op_sel:[0,1,0] op_sel_hi:[0,1,0]
	v_add_f32_dpp v12, v12, v12 row_ror:2 row_mask:0xf bank_mask:0xf bound_ctrl:1
	v_pk_fma_f32 v[48:49], v[28:29], v[66:67], v[48:49] op_sel_hi:[1,0,1]
	v_pk_fma_f32 v[50:51], v[30:31], v[66:67], v[50:51] op_sel_hi:[1,0,1]
	v_add_f32_dpp v12, v12, v12 row_ror:4 row_mask:0xf bank_mask:0xf bound_ctrl:1
	v_fma_mix_f32 v82, v8, v113, v82 op_sel_hi:[0,1,0]
	v_fma_mix_f32 v82, v9, v113, v82 op_sel:[0,1,0] op_sel_hi:[0,1,0]
	v_add_f32_dpp v12, v12, v12 row_ror:8 row_mask:0xf bank_mask:0xf bound_ctrl:1
	v_pk_fma_f32 v[6:7], v[24:25], v[12:13], v[48:49] op_sel_hi:[1,0,1] neg_lo:[1,0,0] neg_hi:[1,0,0]
	v_pk_fma_f32 v[8:9], v[26:27], v[12:13], v[50:51] op_sel_hi:[1,0,1] neg_lo:[1,0,0] neg_hi:[1,0,0]
	ds_read_b128 v[88:91], v10 offset:26880
	ds_read_b128 v[84:87], v10 offset:26624
	ds_read_b128 v[96:99], v10 offset:27392
	ds_read_b128 v[92:95], v10 offset:27136
	s_waitcnt lgkmcnt(4)
	v_fma_mix_f32 v12, v6, v36, v180 op_sel_hi:[0,1,0]
	v_fma_mix_f32 v12, v7, v36, v12 op_sel:[0,1,0] op_sel_hi:[0,1,0]
	v_fma_mix_f32 v12, v8, v37, v12 op_sel_hi:[0,1,0]
	v_fma_mix_f32 v12, v9, v37, v12 op_sel:[0,1,0] op_sel_hi:[0,1,0]
	v_pk_mul_f32 v[48:49], v[6:7], v[32:33]
	v_pk_mul_f32 v[50:51], v[8:9], v[34:35]
	v_add_f32_dpp v12, v12, v12 row_ror:1 row_mask:0xf bank_mask:0xf bound_ctrl:1
	v_fma_mix_f32 v83, v6, v22, v180 op_sel_hi:[0,1,0]
	v_fma_mix_f32 v83, v7, v22, v83 op_sel:[0,1,0] op_sel_hi:[0,1,0]
	v_add_f32_dpp v12, v12, v12 row_ror:2 row_mask:0xf bank_mask:0xf bound_ctrl:1
	v_pk_fma_f32 v[48:49], v[44:45], v[66:67], v[48:49] op_sel:[0,1,0]
	v_pk_fma_f32 v[50:51], v[46:47], v[66:67], v[50:51] op_sel:[0,1,0]
	v_add_f32_dpp v12, v12, v12 row_ror:4 row_mask:0xf bank_mask:0xf bound_ctrl:1
	v_fma_mix_f32 v83, v8, v23, v83 op_sel_hi:[0,1,0]
	v_fma_mix_f32 v83, v9, v23, v83 op_sel:[0,1,0] op_sel_hi:[0,1,0]
	v_add_f32_dpp v12, v12, v12 row_ror:8 row_mask:0xf bank_mask:0xf bound_ctrl:1
	v_pk_fma_f32 v[6:7], v[40:41], v[12:13], v[48:49] op_sel_hi:[1,0,1] neg_lo:[1,0,0] neg_hi:[1,0,0]
	v_pk_fma_f32 v[8:9], v[42:43], v[12:13], v[50:51] op_sel_hi:[1,0,1] neg_lo:[1,0,0] neg_hi:[1,0,0]
	ds_read_b128 v[110:113], v10 offset:27904
	ds_read_b128 v[106:109], v10 offset:27648
	ds_read_b128 v[118:121], v10 offset:28416
	ds_read_b128 v[114:117], v10 offset:28160
	ds_read_b128 v[70:73], v11 offset:1792
	s_waitcnt lgkmcnt(5)
	v_fma_mix_f32 v12, v6, v88, v180 op_sel_hi:[0,1,0]
	v_fma_mix_f32 v12, v7, v88, v12 op_sel:[0,1,0] op_sel_hi:[0,1,0]
	v_fma_mix_f32 v12, v8, v89, v12 op_sel_hi:[0,1,0]
	v_fma_mix_f32 v12, v9, v89, v12 op_sel:[0,1,0] op_sel_hi:[0,1,0]
	v_pk_mul_f32 v[48:49], v[6:7], v[84:85]
	v_pk_mul_f32 v[50:51], v[8:9], v[86:87]
	v_add_f32_dpp v12, v12, v12 row_ror:1 row_mask:0xf bank_mask:0xf bound_ctrl:1
	v_fma_mix_f32 v100, v6, v38, v180 op_sel_hi:[0,1,0]
	v_fma_mix_f32 v100, v7, v38, v100 op_sel:[0,1,0] op_sel_hi:[0,1,0]
	v_add_f32_dpp v12, v12, v12 row_ror:2 row_mask:0xf bank_mask:0xf bound_ctrl:1
	v_pk_fma_f32 v[48:49], v[96:97], v[68:69], v[48:49] op_sel_hi:[1,0,1]
	v_pk_fma_f32 v[50:51], v[98:99], v[68:69], v[50:51] op_sel_hi:[1,0,1]
	v_add_f32_dpp v12, v12, v12 row_ror:4 row_mask:0xf bank_mask:0xf bound_ctrl:1
	v_fma_mix_f32 v100, v8, v39, v100 op_sel_hi:[0,1,0]
	v_fma_mix_f32 v100, v9, v39, v100 op_sel:[0,1,0] op_sel_hi:[0,1,0]
	v_add_f32_dpp v12, v12, v12 row_ror:8 row_mask:0xf bank_mask:0xf bound_ctrl:1
	v_pk_fma_f32 v[6:7], v[92:93], v[12:13], v[48:49] op_sel_hi:[1,0,1] neg_lo:[1,0,0] neg_hi:[1,0,0]
	v_pk_fma_f32 v[8:9], v[94:95], v[12:13], v[50:51] op_sel_hi:[1,0,1] neg_lo:[1,0,0] neg_hi:[1,0,0]
	ds_read_b128 v[20:23], v10 offset:28928
	ds_read_b128 v[16:19], v10 offset:28672
	ds_read_b128 v[28:31], v10 offset:29440
	ds_read_b128 v[24:27], v10 offset:29184
	s_waitcnt lgkmcnt(5)
	v_fma_mix_f32 v12, v6, v110, v180 op_sel_hi:[0,1,0]
	v_fma_mix_f32 v12, v7, v110, v12 op_sel:[0,1,0] op_sel_hi:[0,1,0]
	v_fma_mix_f32 v12, v8, v111, v12 op_sel_hi:[0,1,0]
	v_fma_mix_f32 v12, v9, v111, v12 op_sel:[0,1,0] op_sel_hi:[0,1,0]
	v_pk_mul_f32 v[48:49], v[6:7], v[106:107]
	v_pk_mul_f32 v[50:51], v[8:9], v[108:109]
	v_add_f32_dpp v12, v12, v12 row_ror:1 row_mask:0xf bank_mask:0xf bound_ctrl:1
	v_fma_mix_f32 v101, v6, v90, v180 op_sel_hi:[0,1,0]
	v_fma_mix_f32 v101, v7, v90, v101 op_sel:[0,1,0] op_sel_hi:[0,1,0]
	v_add_f32_dpp v12, v12, v12 row_ror:2 row_mask:0xf bank_mask:0xf bound_ctrl:1
	v_pk_fma_f32 v[48:49], v[118:119], v[68:69], v[48:49] op_sel:[0,1,0]
	v_pk_fma_f32 v[50:51], v[120:121], v[68:69], v[50:51] op_sel:[0,1,0]
	v_add_f32_dpp v12, v12, v12 row_ror:4 row_mask:0xf bank_mask:0xf bound_ctrl:1
	v_fma_mix_f32 v101, v8, v91, v101 op_sel_hi:[0,1,0]
	v_fma_mix_f32 v101, v9, v91, v101 op_sel:[0,1,0] op_sel_hi:[0,1,0]
	v_add_f32_dpp v12, v12, v12 row_ror:8 row_mask:0xf bank_mask:0xf bound_ctrl:1
	v_pk_fma_f32 v[6:7], v[114:115], v[12:13], v[48:49] op_sel_hi:[1,0,1] neg_lo:[1,0,0] neg_hi:[1,0,0]
	v_pk_fma_f32 v[8:9], v[116:117], v[12:13], v[50:51] op_sel_hi:[1,0,1] neg_lo:[1,0,0] neg_hi:[1,0,0]
	ds_read_b128 v[36:39], v10 offset:29952
	ds_read_b128 v[32:35], v10 offset:29696
	ds_read_b128 v[44:47], v10 offset:30464
	ds_read_b128 v[40:43], v10 offset:30208
	s_waitcnt lgkmcnt(4)
	v_fma_mix_f32 v12, v6, v20, v180 op_sel_hi:[0,1,0]
	v_fma_mix_f32 v12, v7, v20, v12 op_sel:[0,1,0] op_sel_hi:[0,1,0]
	v_fma_mix_f32 v12, v8, v21, v12 op_sel_hi:[0,1,0]
	v_fma_mix_f32 v12, v9, v21, v12 op_sel:[0,1,0] op_sel_hi:[0,1,0]
	v_pk_mul_f32 v[48:49], v[6:7], v[16:17]
	v_pk_mul_f32 v[50:51], v[8:9], v[18:19]
	v_add_f32_dpp v12, v12, v12 row_ror:1 row_mask:0xf bank_mask:0xf bound_ctrl:1
	v_fma_mix_f32 v102, v6, v112, v180 op_sel_hi:[0,1,0]
	v_fma_mix_f32 v102, v7, v112, v102 op_sel:[0,1,0] op_sel_hi:[0,1,0]
	v_add_f32_dpp v12, v12, v12 row_ror:2 row_mask:0xf bank_mask:0xf bound_ctrl:1
	v_pk_fma_f32 v[48:49], v[28:29], v[70:71], v[48:49] op_sel_hi:[1,0,1]
	v_pk_fma_f32 v[50:51], v[30:31], v[70:71], v[50:51] op_sel_hi:[1,0,1]
	v_add_f32_dpp v12, v12, v12 row_ror:4 row_mask:0xf bank_mask:0xf bound_ctrl:1
	v_fma_mix_f32 v102, v8, v113, v102 op_sel_hi:[0,1,0]
	v_fma_mix_f32 v102, v9, v113, v102 op_sel:[0,1,0] op_sel_hi:[0,1,0]
	v_add_f32_dpp v12, v12, v12 row_ror:8 row_mask:0xf bank_mask:0xf bound_ctrl:1
	v_pk_fma_f32 v[6:7], v[24:25], v[12:13], v[48:49] op_sel_hi:[1,0,1] neg_lo:[1,0,0] neg_hi:[1,0,0]
	v_pk_fma_f32 v[8:9], v[26:27], v[12:13], v[50:51] op_sel_hi:[1,0,1] neg_lo:[1,0,0] neg_hi:[1,0,0]
	ds_read_b128 v[88:91], v10 offset:30976
	ds_read_b128 v[84:87], v10 offset:30720
	ds_read_b128 v[96:99], v10 offset:31488
	ds_read_b128 v[92:95], v10 offset:31232
	s_waitcnt lgkmcnt(4)
	v_fma_mix_f32 v12, v6, v36, v180 op_sel_hi:[0,1,0]
	v_fma_mix_f32 v12, v7, v36, v12 op_sel:[0,1,0] op_sel_hi:[0,1,0]
	v_fma_mix_f32 v12, v8, v37, v12 op_sel_hi:[0,1,0]
	v_fma_mix_f32 v12, v9, v37, v12 op_sel:[0,1,0] op_sel_hi:[0,1,0]
	v_pk_mul_f32 v[48:49], v[6:7], v[32:33]
	v_pk_mul_f32 v[50:51], v[8:9], v[34:35]
	v_add_f32_dpp v12, v12, v12 row_ror:1 row_mask:0xf bank_mask:0xf bound_ctrl:1
	v_fma_mix_f32 v103, v6, v22, v180 op_sel_hi:[0,1,0]
	v_fma_mix_f32 v103, v7, v22, v103 op_sel:[0,1,0] op_sel_hi:[0,1,0]
	v_add_f32_dpp v12, v12, v12 row_ror:2 row_mask:0xf bank_mask:0xf bound_ctrl:1
	v_pk_fma_f32 v[48:49], v[44:45], v[70:71], v[48:49] op_sel:[0,1,0]
	v_pk_fma_f32 v[50:51], v[46:47], v[70:71], v[50:51] op_sel:[0,1,0]
	v_add_f32_dpp v12, v12, v12 row_ror:4 row_mask:0xf bank_mask:0xf bound_ctrl:1
	v_fma_mix_f32 v103, v8, v23, v103 op_sel_hi:[0,1,0]
	v_fma_mix_f32 v103, v9, v23, v103 op_sel:[0,1,0] op_sel_hi:[0,1,0]
	v_add_f32_dpp v12, v12, v12 row_ror:8 row_mask:0xf bank_mask:0xf bound_ctrl:1
	v_pk_fma_f32 v[6:7], v[40:41], v[12:13], v[48:49] op_sel_hi:[1,0,1] neg_lo:[1,0,0] neg_hi:[1,0,0]
	v_pk_fma_f32 v[8:9], v[42:43], v[12:13], v[50:51] op_sel_hi:[1,0,1] neg_lo:[1,0,0] neg_hi:[1,0,0]
	ds_read_b128 v[110:113], v10 offset:32000
	ds_read_b128 v[106:109], v10 offset:31744
	ds_read_b128 v[118:121], v10 offset:32512
	ds_read_b128 v[114:117], v10 offset:32256
	ds_read_b128 v[66:69], v11 offset:2048
	s_waitcnt lgkmcnt(5)
	v_fma_mix_f32 v12, v6, v88, v180 op_sel_hi:[0,1,0]
	v_fma_mix_f32 v12, v7, v88, v12 op_sel:[0,1,0] op_sel_hi:[0,1,0]
	v_fma_mix_f32 v12, v8, v89, v12 op_sel_hi:[0,1,0]
	v_fma_mix_f32 v12, v9, v89, v12 op_sel:[0,1,0] op_sel_hi:[0,1,0]
	v_pk_mul_f32 v[48:49], v[6:7], v[84:85]
	v_pk_mul_f32 v[50:51], v[8:9], v[86:87]
	v_add_f32_dpp v12, v12, v12 row_ror:1 row_mask:0xf bank_mask:0xf bound_ctrl:1
	v_fma_mix_f32 v104, v6, v38, v180 op_sel_hi:[0,1,0]
	v_fma_mix_f32 v104, v7, v38, v104 op_sel:[0,1,0] op_sel_hi:[0,1,0]
	v_add_f32_dpp v12, v12, v12 row_ror:2 row_mask:0xf bank_mask:0xf bound_ctrl:1
	v_pk_fma_f32 v[48:49], v[96:97], v[72:73], v[48:49] op_sel_hi:[1,0,1]
	v_pk_fma_f32 v[50:51], v[98:99], v[72:73], v[50:51] op_sel_hi:[1,0,1]
	v_add_f32_dpp v12, v12, v12 row_ror:4 row_mask:0xf bank_mask:0xf bound_ctrl:1
	v_fma_mix_f32 v104, v8, v39, v104 op_sel_hi:[0,1,0]
	v_fma_mix_f32 v104, v9, v39, v104 op_sel:[0,1,0] op_sel_hi:[0,1,0]
	v_add_f32_dpp v12, v12, v12 row_ror:8 row_mask:0xf bank_mask:0xf bound_ctrl:1
	v_pk_fma_f32 v[6:7], v[92:93], v[12:13], v[48:49] op_sel_hi:[1,0,1] neg_lo:[1,0,0] neg_hi:[1,0,0]
	v_pk_fma_f32 v[8:9], v[94:95], v[12:13], v[50:51] op_sel_hi:[1,0,1] neg_lo:[1,0,0] neg_hi:[1,0,0]
	ds_read_b128 v[20:23], v10 offset:33024
	ds_read_b128 v[16:19], v10 offset:32768
	ds_read_b128 v[28:31], v10 offset:33536
	ds_read_b128 v[24:27], v10 offset:33280
	s_waitcnt lgkmcnt(5)
	v_fma_mix_f32 v12, v6, v110, v180 op_sel_hi:[0,1,0]
	v_fma_mix_f32 v12, v7, v110, v12 op_sel:[0,1,0] op_sel_hi:[0,1,0]
	v_fma_mix_f32 v12, v8, v111, v12 op_sel_hi:[0,1,0]
	v_fma_mix_f32 v12, v9, v111, v12 op_sel:[0,1,0] op_sel_hi:[0,1,0]
	v_pk_mul_f32 v[48:49], v[6:7], v[106:107]
	v_pk_mul_f32 v[50:51], v[8:9], v[108:109]
	v_add_f32_dpp v12, v12, v12 row_ror:1 row_mask:0xf bank_mask:0xf bound_ctrl:1
	v_fma_mix_f32 v105, v6, v90, v180 op_sel_hi:[0,1,0]
	v_fma_mix_f32 v105, v7, v90, v105 op_sel:[0,1,0] op_sel_hi:[0,1,0]
	v_add_f32_dpp v12, v12, v12 row_ror:2 row_mask:0xf bank_mask:0xf bound_ctrl:1
	v_pk_fma_f32 v[48:49], v[118:119], v[72:73], v[48:49] op_sel:[0,1,0]
	v_pk_fma_f32 v[50:51], v[120:121], v[72:73], v[50:51] op_sel:[0,1,0]
	v_add_f32_dpp v12, v12, v12 row_ror:4 row_mask:0xf bank_mask:0xf bound_ctrl:1
	v_fma_mix_f32 v105, v8, v91, v105 op_sel_hi:[0,1,0]
	v_fma_mix_f32 v105, v9, v91, v105 op_sel:[0,1,0] op_sel_hi:[0,1,0]
	v_add_f32_dpp v12, v12, v12 row_ror:8 row_mask:0xf bank_mask:0xf bound_ctrl:1
	v_pk_fma_f32 v[6:7], v[114:115], v[12:13], v[48:49] op_sel_hi:[1,0,1] neg_lo:[1,0,0] neg_hi:[1,0,0]
	v_pk_fma_f32 v[8:9], v[116:117], v[12:13], v[50:51] op_sel_hi:[1,0,1] neg_lo:[1,0,0] neg_hi:[1,0,0]
	ds_read_b128 v[36:39], v10 offset:34048
	ds_read_b128 v[32:35], v10 offset:33792
	ds_read_b128 v[44:47], v10 offset:34560
	ds_read_b128 v[40:43], v10 offset:34304
	s_waitcnt lgkmcnt(4)
	v_fma_mix_f32 v12, v6, v20, v180 op_sel_hi:[0,1,0]
	v_fma_mix_f32 v12, v7, v20, v12 op_sel:[0,1,0] op_sel_hi:[0,1,0]
	v_fma_mix_f32 v12, v8, v21, v12 op_sel_hi:[0,1,0]
	v_fma_mix_f32 v12, v9, v21, v12 op_sel:[0,1,0] op_sel_hi:[0,1,0]
	v_pk_mul_f32 v[48:49], v[6:7], v[16:17]
	v_pk_mul_f32 v[50:51], v[8:9], v[18:19]
	v_add_f32_dpp v12, v12, v12 row_ror:1 row_mask:0xf bank_mask:0xf bound_ctrl:1
	v_fma_mix_f32 v61, v6, v112, v180 op_sel_hi:[0,1,0]
	v_fma_mix_f32 v61, v7, v112, v61 op_sel:[0,1,0] op_sel_hi:[0,1,0]
	v_add_f32_dpp v12, v12, v12 row_ror:2 row_mask:0xf bank_mask:0xf bound_ctrl:1
	v_pk_fma_f32 v[48:49], v[28:29], v[66:67], v[48:49] op_sel_hi:[1,0,1]
	v_pk_fma_f32 v[50:51], v[30:31], v[66:67], v[50:51] op_sel_hi:[1,0,1]
	v_add_f32_dpp v12, v12, v12 row_ror:4 row_mask:0xf bank_mask:0xf bound_ctrl:1
	v_fma_mix_f32 v61, v8, v113, v61 op_sel_hi:[0,1,0]
	v_fma_mix_f32 v61, v9, v113, v61 op_sel:[0,1,0] op_sel_hi:[0,1,0]
	v_add_f32_dpp v12, v12, v12 row_ror:8 row_mask:0xf bank_mask:0xf bound_ctrl:1
	v_pk_fma_f32 v[6:7], v[24:25], v[12:13], v[48:49] op_sel_hi:[1,0,1] neg_lo:[1,0,0] neg_hi:[1,0,0]
	v_pk_fma_f32 v[8:9], v[26:27], v[12:13], v[50:51] op_sel_hi:[1,0,1] neg_lo:[1,0,0] neg_hi:[1,0,0]
	ds_read_b128 v[88:91], v10 offset:35072
	ds_read_b128 v[84:87], v10 offset:34816
	ds_read_b128 v[96:99], v10 offset:35584
	ds_read_b128 v[92:95], v10 offset:35328
	v_add_f32_dpp v83, v83, v83 row_ror:8 row_mask:0xf bank_mask:0xc
	v_add_f32_dpp v83, v52, v52 row_ror:8 row_mask:0xf bank_mask:0x3
	v_add_f32_dpp v100, v100, v100 row_ror:8 row_mask:0xf bank_mask:0xc
	v_add_f32_dpp v100, v53, v53 row_ror:8 row_mask:0xf bank_mask:0x3
	v_add_f32_dpp v101, v101, v101 row_ror:8 row_mask:0xf bank_mask:0xc
	v_add_f32_dpp v101, v54, v54 row_ror:8 row_mask:0xf bank_mask:0x3
	v_add_f32_dpp v102, v102, v102 row_ror:8 row_mask:0xf bank_mask:0xc
	v_add_f32_dpp v102, v55, v55 row_ror:8 row_mask:0xf bank_mask:0x3
	v_add_f32_dpp v103, v103, v103 row_ror:8 row_mask:0xf bank_mask:0xc
	v_add_f32_dpp v103, v56, v56 row_ror:8 row_mask:0xf bank_mask:0x3
	v_add_f32_dpp v104, v104, v104 row_ror:8 row_mask:0xf bank_mask:0xc
	v_add_f32_dpp v104, v57, v57 row_ror:8 row_mask:0xf bank_mask:0x3
	v_add_f32_dpp v105, v105, v105 row_ror:8 row_mask:0xf bank_mask:0xc
	v_add_f32_dpp v105, v81, v81 row_ror:8 row_mask:0xf bank_mask:0x3
	v_add_f32_dpp v61, v61, v61 row_ror:8 row_mask:0xf bank_mask:0xc
	v_add_f32_dpp v61, v82, v82 row_ror:8 row_mask:0xf bank_mask:0x3
	v_add_f32_dpp v103, v103, v103 row_ror:4 row_mask:0xf bank_mask:0xa
	v_add_f32_dpp v103, v83, v83 row_ror:12 row_mask:0xf bank_mask:0x5
	v_add_f32_dpp v104, v104, v104 row_ror:4 row_mask:0xf bank_mask:0xa
	v_add_f32_dpp v104, v100, v100 row_ror:12 row_mask:0xf bank_mask:0x5
	v_add_f32_dpp v105, v105, v105 row_ror:4 row_mask:0xf bank_mask:0xa
	v_add_f32_dpp v105, v101, v101 row_ror:12 row_mask:0xf bank_mask:0x5
	v_add_f32_dpp v61, v61, v61 row_ror:4 row_mask:0xf bank_mask:0xa
	v_add_f32_dpp v61, v102, v102 row_ror:12 row_mask:0xf bank_mask:0x5
	v_cndmask_b32_e64 v62, v105, v103, s[38:39]
	v_cndmask_b32_e64 v63, v103, v105, s[38:39]
	v_cndmask_b32_e64 v64, v61, v104, s[38:39]
	v_cndmask_b32_e64 v65, v104, v61, s[38:39]
	v_add_f32_dpp v62, v63, v62 quad_perm:[2,3,0,1] row_mask:0xf bank_mask:0xf bound_ctrl:1
	s_nop 0
	v_add_f32_dpp v63, v65, v64 quad_perm:[2,3,0,1] row_mask:0xf bank_mask:0xf bound_ctrl:1
	v_cndmask_b32_e64 v65, v63, v62, s[40:41]
	v_cndmask_b32_e64 v62, v62, v63, s[40:41]
	s_nop 1
	v_add_f32_dpp v62, v62, v65 quad_perm:[1,0,3,2] row_mask:0xf bank_mask:0xf bound_ctrl:1
	v_cvt_pk_bf16_f32 v62, v62, v62
	global_store_short v[2:3], v62, off
	v_lshl_add_u64 v[2:3], v[2:3], 0, s[84:85]
	s_waitcnt lgkmcnt(4)
	v_fma_mix_f32 v12, v6, v36, v180 op_sel_hi:[0,1,0]
	v_fma_mix_f32 v12, v7, v36, v12 op_sel:[0,1,0] op_sel_hi:[0,1,0]
	v_fma_mix_f32 v12, v8, v37, v12 op_sel_hi:[0,1,0]
	v_fma_mix_f32 v12, v9, v37, v12 op_sel:[0,1,0] op_sel_hi:[0,1,0]
	v_pk_mul_f32 v[48:49], v[6:7], v[32:33]
	v_pk_mul_f32 v[50:51], v[8:9], v[34:35]
	v_add_f32_dpp v12, v12, v12 row_ror:1 row_mask:0xf bank_mask:0xf bound_ctrl:1
	v_fma_mix_f32 v52, v6, v22, v180 op_sel_hi:[0,1,0]
	v_fma_mix_f32 v52, v7, v22, v52 op_sel:[0,1,0] op_sel_hi:[0,1,0]
	v_add_f32_dpp v12, v12, v12 row_ror:2 row_mask:0xf bank_mask:0xf bound_ctrl:1
	v_pk_fma_f32 v[48:49], v[44:45], v[66:67], v[48:49] op_sel:[0,1,0]
	v_pk_fma_f32 v[50:51], v[46:47], v[66:67], v[50:51] op_sel:[0,1,0]
	v_add_f32_dpp v12, v12, v12 row_ror:4 row_mask:0xf bank_mask:0xf bound_ctrl:1
	v_fma_mix_f32 v52, v8, v23, v52 op_sel_hi:[0,1,0]
	v_fma_mix_f32 v52, v9, v23, v52 op_sel:[0,1,0] op_sel_hi:[0,1,0]
	v_add_f32_dpp v12, v12, v12 row_ror:8 row_mask:0xf bank_mask:0xf bound_ctrl:1
	v_pk_fma_f32 v[6:7], v[40:41], v[12:13], v[48:49] op_sel_hi:[1,0,1] neg_lo:[1,0,0] neg_hi:[1,0,0]
	v_pk_fma_f32 v[8:9], v[42:43], v[12:13], v[50:51] op_sel_hi:[1,0,1] neg_lo:[1,0,0] neg_hi:[1,0,0]
	ds_read_b128 v[110:113], v10 offset:36096
	ds_read_b128 v[106:109], v10 offset:35840
	ds_read_b128 v[118:121], v10 offset:36608
	ds_read_b128 v[114:117], v10 offset:36352
	ds_read_b128 v[70:73], v11 offset:2304
	s_waitcnt lgkmcnt(5)
	v_fma_mix_f32 v12, v6, v88, v180 op_sel_hi:[0,1,0]
	v_fma_mix_f32 v12, v7, v88, v12 op_sel:[0,1,0] op_sel_hi:[0,1,0]
	v_fma_mix_f32 v12, v8, v89, v12 op_sel_hi:[0,1,0]
	v_fma_mix_f32 v12, v9, v89, v12 op_sel:[0,1,0] op_sel_hi:[0,1,0]
	v_pk_mul_f32 v[48:49], v[6:7], v[84:85]
	v_pk_mul_f32 v[50:51], v[8:9], v[86:87]
	v_add_f32_dpp v12, v12, v12 row_ror:1 row_mask:0xf bank_mask:0xf bound_ctrl:1
	v_fma_mix_f32 v53, v6, v38, v180 op_sel_hi:[0,1,0]
	v_fma_mix_f32 v53, v7, v38, v53 op_sel:[0,1,0] op_sel_hi:[0,1,0]
	v_add_f32_dpp v12, v12, v12 row_ror:2 row_mask:0xf bank_mask:0xf bound_ctrl:1
	v_pk_fma_f32 v[48:49], v[96:97], v[68:69], v[48:49] op_sel_hi:[1,0,1]
	v_pk_fma_f32 v[50:51], v[98:99], v[68:69], v[50:51] op_sel_hi:[1,0,1]
	v_add_f32_dpp v12, v12, v12 row_ror:4 row_mask:0xf bank_mask:0xf bound_ctrl:1
	v_fma_mix_f32 v53, v8, v39, v53 op_sel_hi:[0,1,0]
	v_fma_mix_f32 v53, v9, v39, v53 op_sel:[0,1,0] op_sel_hi:[0,1,0]
	v_add_f32_dpp v12, v12, v12 row_ror:8 row_mask:0xf bank_mask:0xf bound_ctrl:1
	v_pk_fma_f32 v[6:7], v[92:93], v[12:13], v[48:49] op_sel_hi:[1,0,1] neg_lo:[1,0,0] neg_hi:[1,0,0]
	v_pk_fma_f32 v[8:9], v[94:95], v[12:13], v[50:51] op_sel_hi:[1,0,1] neg_lo:[1,0,0] neg_hi:[1,0,0]
	ds_read_b128 v[20:23], v10 offset:37120
	ds_read_b128 v[16:19], v10 offset:36864
	ds_read_b128 v[28:31], v10 offset:37632
	ds_read_b128 v[24:27], v10 offset:37376
	s_waitcnt lgkmcnt(5)
	v_fma_mix_f32 v12, v6, v110, v180 op_sel_hi:[0,1,0]
	v_fma_mix_f32 v12, v7, v110, v12 op_sel:[0,1,0] op_sel_hi:[0,1,0]
	v_fma_mix_f32 v12, v8, v111, v12 op_sel_hi:[0,1,0]
	v_fma_mix_f32 v12, v9, v111, v12 op_sel:[0,1,0] op_sel_hi:[0,1,0]
	v_pk_mul_f32 v[48:49], v[6:7], v[106:107]
	v_pk_mul_f32 v[50:51], v[8:9], v[108:109]
	v_add_f32_dpp v12, v12, v12 row_ror:1 row_mask:0xf bank_mask:0xf bound_ctrl:1
	v_fma_mix_f32 v54, v6, v90, v180 op_sel_hi:[0,1,0]
	v_fma_mix_f32 v54, v7, v90, v54 op_sel:[0,1,0] op_sel_hi:[0,1,0]
	v_add_f32_dpp v12, v12, v12 row_ror:2 row_mask:0xf bank_mask:0xf bound_ctrl:1
	v_pk_fma_f32 v[48:49], v[118:119], v[68:69], v[48:49] op_sel:[0,1,0]
	v_pk_fma_f32 v[50:51], v[120:121], v[68:69], v[50:51] op_sel:[0,1,0]
	v_add_f32_dpp v12, v12, v12 row_ror:4 row_mask:0xf bank_mask:0xf bound_ctrl:1
	v_fma_mix_f32 v54, v8, v91, v54 op_sel_hi:[0,1,0]
	v_fma_mix_f32 v54, v9, v91, v54 op_sel:[0,1,0] op_sel_hi:[0,1,0]
	v_add_f32_dpp v12, v12, v12 row_ror:8 row_mask:0xf bank_mask:0xf bound_ctrl:1
	v_pk_fma_f32 v[6:7], v[114:115], v[12:13], v[48:49] op_sel_hi:[1,0,1] neg_lo:[1,0,0] neg_hi:[1,0,0]
	v_pk_fma_f32 v[8:9], v[116:117], v[12:13], v[50:51] op_sel_hi:[1,0,1] neg_lo:[1,0,0] neg_hi:[1,0,0]
	ds_read_b128 v[36:39], v10 offset:38144
	ds_read_b128 v[32:35], v10 offset:37888
	ds_read_b128 v[44:47], v10 offset:38656
	ds_read_b128 v[40:43], v10 offset:38400
	s_waitcnt lgkmcnt(4)
	v_fma_mix_f32 v12, v6, v20, v180 op_sel_hi:[0,1,0]
	v_fma_mix_f32 v12, v7, v20, v12 op_sel:[0,1,0] op_sel_hi:[0,1,0]
	v_fma_mix_f32 v12, v8, v21, v12 op_sel_hi:[0,1,0]
	v_fma_mix_f32 v12, v9, v21, v12 op_sel:[0,1,0] op_sel_hi:[0,1,0]
	v_pk_mul_f32 v[48:49], v[6:7], v[16:17]
	v_pk_mul_f32 v[50:51], v[8:9], v[18:19]
	v_add_f32_dpp v12, v12, v12 row_ror:1 row_mask:0xf bank_mask:0xf bound_ctrl:1
	v_fma_mix_f32 v55, v6, v112, v180 op_sel_hi:[0,1,0]
	v_fma_mix_f32 v55, v7, v112, v55 op_sel:[0,1,0] op_sel_hi:[0,1,0]
	v_add_f32_dpp v12, v12, v12 row_ror:2 row_mask:0xf bank_mask:0xf bound_ctrl:1
	v_pk_fma_f32 v[48:49], v[28:29], v[70:71], v[48:49] op_sel_hi:[1,0,1]
	v_pk_fma_f32 v[50:51], v[30:31], v[70:71], v[50:51] op_sel_hi:[1,0,1]
	v_add_f32_dpp v12, v12, v12 row_ror:4 row_mask:0xf bank_mask:0xf bound_ctrl:1
	v_fma_mix_f32 v55, v8, v113, v55 op_sel_hi:[0,1,0]
	v_fma_mix_f32 v55, v9, v113, v55 op_sel:[0,1,0] op_sel_hi:[0,1,0]
	v_add_f32_dpp v12, v12, v12 row_ror:8 row_mask:0xf bank_mask:0xf bound_ctrl:1
	v_pk_fma_f32 v[6:7], v[24:25], v[12:13], v[48:49] op_sel_hi:[1,0,1] neg_lo:[1,0,0] neg_hi:[1,0,0]
	v_pk_fma_f32 v[8:9], v[26:27], v[12:13], v[50:51] op_sel_hi:[1,0,1] neg_lo:[1,0,0] neg_hi:[1,0,0]
	ds_read_b128 v[88:91], v10 offset:39168
	ds_read_b128 v[84:87], v10 offset:38912
	ds_read_b128 v[96:99], v10 offset:39680
	ds_read_b128 v[92:95], v10 offset:39424
	s_waitcnt lgkmcnt(4)
	v_fma_mix_f32 v12, v6, v36, v180 op_sel_hi:[0,1,0]
	v_fma_mix_f32 v12, v7, v36, v12 op_sel:[0,1,0] op_sel_hi:[0,1,0]
	v_fma_mix_f32 v12, v8, v37, v12 op_sel_hi:[0,1,0]
	v_fma_mix_f32 v12, v9, v37, v12 op_sel:[0,1,0] op_sel_hi:[0,1,0]
	v_pk_mul_f32 v[48:49], v[6:7], v[32:33]
	v_pk_mul_f32 v[50:51], v[8:9], v[34:35]
	v_add_f32_dpp v12, v12, v12 row_ror:1 row_mask:0xf bank_mask:0xf bound_ctrl:1
	v_fma_mix_f32 v56, v6, v22, v180 op_sel_hi:[0,1,0]
	v_fma_mix_f32 v56, v7, v22, v56 op_sel:[0,1,0] op_sel_hi:[0,1,0]
	v_add_f32_dpp v12, v12, v12 row_ror:2 row_mask:0xf bank_mask:0xf bound_ctrl:1
	v_pk_fma_f32 v[48:49], v[44:45], v[70:71], v[48:49] op_sel:[0,1,0]
	v_pk_fma_f32 v[50:51], v[46:47], v[70:71], v[50:51] op_sel:[0,1,0]
	v_add_f32_dpp v12, v12, v12 row_ror:4 row_mask:0xf bank_mask:0xf bound_ctrl:1
	v_fma_mix_f32 v56, v8, v23, v56 op_sel_hi:[0,1,0]
	v_fma_mix_f32 v56, v9, v23, v56 op_sel:[0,1,0] op_sel_hi:[0,1,0]
	v_add_f32_dpp v12, v12, v12 row_ror:8 row_mask:0xf bank_mask:0xf bound_ctrl:1
	v_pk_fma_f32 v[6:7], v[40:41], v[12:13], v[48:49] op_sel_hi:[1,0,1] neg_lo:[1,0,0] neg_hi:[1,0,0]
	v_pk_fma_f32 v[8:9], v[42:43], v[12:13], v[50:51] op_sel_hi:[1,0,1] neg_lo:[1,0,0] neg_hi:[1,0,0]
	ds_read_b128 v[110:113], v10 offset:40192
	ds_read_b128 v[106:109], v10 offset:39936
	ds_read_b128 v[118:121], v10 offset:40704
	ds_read_b128 v[114:117], v10 offset:40448
	ds_read_b128 v[66:69], v11 offset:2560
	s_waitcnt lgkmcnt(5)
	v_fma_mix_f32 v12, v6, v88, v180 op_sel_hi:[0,1,0]
	v_fma_mix_f32 v12, v7, v88, v12 op_sel:[0,1,0] op_sel_hi:[0,1,0]
	v_fma_mix_f32 v12, v8, v89, v12 op_sel_hi:[0,1,0]
	v_fma_mix_f32 v12, v9, v89, v12 op_sel:[0,1,0] op_sel_hi:[0,1,0]
	v_pk_mul_f32 v[48:49], v[6:7], v[84:85]
	v_pk_mul_f32 v[50:51], v[8:9], v[86:87]
	v_add_f32_dpp v12, v12, v12 row_ror:1 row_mask:0xf bank_mask:0xf bound_ctrl:1
	v_fma_mix_f32 v57, v6, v38, v180 op_sel_hi:[0,1,0]
	v_fma_mix_f32 v57, v7, v38, v57 op_sel:[0,1,0] op_sel_hi:[0,1,0]
	v_add_f32_dpp v12, v12, v12 row_ror:2 row_mask:0xf bank_mask:0xf bound_ctrl:1
	v_pk_fma_f32 v[48:49], v[96:97], v[72:73], v[48:49] op_sel_hi:[1,0,1]
	v_pk_fma_f32 v[50:51], v[98:99], v[72:73], v[50:51] op_sel_hi:[1,0,1]
	v_add_f32_dpp v12, v12, v12 row_ror:4 row_mask:0xf bank_mask:0xf bound_ctrl:1
	v_fma_mix_f32 v57, v8, v39, v57 op_sel_hi:[0,1,0]
	v_fma_mix_f32 v57, v9, v39, v57 op_sel:[0,1,0] op_sel_hi:[0,1,0]
	v_add_f32_dpp v12, v12, v12 row_ror:8 row_mask:0xf bank_mask:0xf bound_ctrl:1
	v_pk_fma_f32 v[6:7], v[92:93], v[12:13], v[48:49] op_sel_hi:[1,0,1] neg_lo:[1,0,0] neg_hi:[1,0,0]
	v_pk_fma_f32 v[8:9], v[94:95], v[12:13], v[50:51] op_sel_hi:[1,0,1] neg_lo:[1,0,0] neg_hi:[1,0,0]
	ds_read_b128 v[20:23], v10 offset:41216
	ds_read_b128 v[16:19], v10 offset:40960
	ds_read_b128 v[28:31], v10 offset:41728
	ds_read_b128 v[24:27], v10 offset:41472
	s_waitcnt lgkmcnt(5)
	v_fma_mix_f32 v12, v6, v110, v180 op_sel_hi:[0,1,0]
	v_fma_mix_f32 v12, v7, v110, v12 op_sel:[0,1,0] op_sel_hi:[0,1,0]
	v_fma_mix_f32 v12, v8, v111, v12 op_sel_hi:[0,1,0]
	v_fma_mix_f32 v12, v9, v111, v12 op_sel:[0,1,0] op_sel_hi:[0,1,0]
	v_pk_mul_f32 v[48:49], v[6:7], v[106:107]
	v_pk_mul_f32 v[50:51], v[8:9], v[108:109]
	v_add_f32_dpp v12, v12, v12 row_ror:1 row_mask:0xf bank_mask:0xf bound_ctrl:1
	v_fma_mix_f32 v81, v6, v90, v180 op_sel_hi:[0,1,0]
	v_fma_mix_f32 v81, v7, v90, v81 op_sel:[0,1,0] op_sel_hi:[0,1,0]
	v_add_f32_dpp v12, v12, v12 row_ror:2 row_mask:0xf bank_mask:0xf bound_ctrl:1
	v_pk_fma_f32 v[48:49], v[118:119], v[72:73], v[48:49] op_sel:[0,1,0]
	v_pk_fma_f32 v[50:51], v[120:121], v[72:73], v[50:51] op_sel:[0,1,0]
	v_add_f32_dpp v12, v12, v12 row_ror:4 row_mask:0xf bank_mask:0xf bound_ctrl:1
	v_fma_mix_f32 v81, v8, v91, v81 op_sel_hi:[0,1,0]
	v_fma_mix_f32 v81, v9, v91, v81 op_sel:[0,1,0] op_sel_hi:[0,1,0]
	v_add_f32_dpp v12, v12, v12 row_ror:8 row_mask:0xf bank_mask:0xf bound_ctrl:1
	v_pk_fma_f32 v[6:7], v[114:115], v[12:13], v[48:49] op_sel_hi:[1,0,1] neg_lo:[1,0,0] neg_hi:[1,0,0]
	v_pk_fma_f32 v[8:9], v[116:117], v[12:13], v[50:51] op_sel_hi:[1,0,1] neg_lo:[1,0,0] neg_hi:[1,0,0]
	ds_read_b128 v[36:39], v10 offset:42240
	ds_read_b128 v[32:35], v10 offset:41984
	ds_read_b128 v[44:47], v10 offset:42752
	ds_read_b128 v[40:43], v10 offset:42496
	s_waitcnt lgkmcnt(4)
	v_fma_mix_f32 v12, v6, v20, v180 op_sel_hi:[0,1,0]
	v_fma_mix_f32 v12, v7, v20, v12 op_sel:[0,1,0] op_sel_hi:[0,1,0]
	v_fma_mix_f32 v12, v8, v21, v12 op_sel_hi:[0,1,0]
	v_fma_mix_f32 v12, v9, v21, v12 op_sel:[0,1,0] op_sel_hi:[0,1,0]
	v_pk_mul_f32 v[48:49], v[6:7], v[16:17]
	v_pk_mul_f32 v[50:51], v[8:9], v[18:19]
	v_add_f32_dpp v12, v12, v12 row_ror:1 row_mask:0xf bank_mask:0xf bound_ctrl:1
	v_fma_mix_f32 v82, v6, v112, v180 op_sel_hi:[0,1,0]
	v_fma_mix_f32 v82, v7, v112, v82 op_sel:[0,1,0] op_sel_hi:[0,1,0]
	v_add_f32_dpp v12, v12, v12 row_ror:2 row_mask:0xf bank_mask:0xf bound_ctrl:1
	v_pk_fma_f32 v[48:49], v[28:29], v[66:67], v[48:49] op_sel_hi:[1,0,1]
	v_pk_fma_f32 v[50:51], v[30:31], v[66:67], v[50:51] op_sel_hi:[1,0,1]
	v_add_f32_dpp v12, v12, v12 row_ror:4 row_mask:0xf bank_mask:0xf bound_ctrl:1
	v_fma_mix_f32 v82, v8, v113, v82 op_sel_hi:[0,1,0]
	v_fma_mix_f32 v82, v9, v113, v82 op_sel:[0,1,0] op_sel_hi:[0,1,0]
	v_add_f32_dpp v12, v12, v12 row_ror:8 row_mask:0xf bank_mask:0xf bound_ctrl:1
	v_pk_fma_f32 v[6:7], v[24:25], v[12:13], v[48:49] op_sel_hi:[1,0,1] neg_lo:[1,0,0] neg_hi:[1,0,0]
	v_pk_fma_f32 v[8:9], v[26:27], v[12:13], v[50:51] op_sel_hi:[1,0,1] neg_lo:[1,0,0] neg_hi:[1,0,0]
	ds_read_b128 v[88:91], v10 offset:43264
	ds_read_b128 v[84:87], v10 offset:43008
	ds_read_b128 v[96:99], v10 offset:43776
	ds_read_b128 v[92:95], v10 offset:43520
	s_waitcnt lgkmcnt(4)
	v_fma_mix_f32 v12, v6, v36, v180 op_sel_hi:[0,1,0]
	v_fma_mix_f32 v12, v7, v36, v12 op_sel:[0,1,0] op_sel_hi:[0,1,0]
	v_fma_mix_f32 v12, v8, v37, v12 op_sel_hi:[0,1,0]
	v_fma_mix_f32 v12, v9, v37, v12 op_sel:[0,1,0] op_sel_hi:[0,1,0]
	v_pk_mul_f32 v[48:49], v[6:7], v[32:33]
	v_pk_mul_f32 v[50:51], v[8:9], v[34:35]
	v_add_f32_dpp v12, v12, v12 row_ror:1 row_mask:0xf bank_mask:0xf bound_ctrl:1
	v_fma_mix_f32 v83, v6, v22, v180 op_sel_hi:[0,1,0]
	v_fma_mix_f32 v83, v7, v22, v83 op_sel:[0,1,0] op_sel_hi:[0,1,0]
	v_add_f32_dpp v12, v12, v12 row_ror:2 row_mask:0xf bank_mask:0xf bound_ctrl:1
	v_pk_fma_f32 v[48:49], v[44:45], v[66:67], v[48:49] op_sel:[0,1,0]
	v_pk_fma_f32 v[50:51], v[46:47], v[66:67], v[50:51] op_sel:[0,1,0]
	v_add_f32_dpp v12, v12, v12 row_ror:4 row_mask:0xf bank_mask:0xf bound_ctrl:1
	v_fma_mix_f32 v83, v8, v23, v83 op_sel_hi:[0,1,0]
	v_fma_mix_f32 v83, v9, v23, v83 op_sel:[0,1,0] op_sel_hi:[0,1,0]
	v_add_f32_dpp v12, v12, v12 row_ror:8 row_mask:0xf bank_mask:0xf bound_ctrl:1
	v_pk_fma_f32 v[6:7], v[40:41], v[12:13], v[48:49] op_sel_hi:[1,0,1] neg_lo:[1,0,0] neg_hi:[1,0,0]
	v_pk_fma_f32 v[8:9], v[42:43], v[12:13], v[50:51] op_sel_hi:[1,0,1] neg_lo:[1,0,0] neg_hi:[1,0,0]
	ds_read_b128 v[110:113], v10 offset:44288
	ds_read_b128 v[106:109], v10 offset:44032
	ds_read_b128 v[118:121], v10 offset:44800
	ds_read_b128 v[114:117], v10 offset:44544
	ds_read_b128 v[70:73], v11 offset:2816
	s_waitcnt lgkmcnt(5)
	v_fma_mix_f32 v12, v6, v88, v180 op_sel_hi:[0,1,0]
	v_fma_mix_f32 v12, v7, v88, v12 op_sel:[0,1,0] op_sel_hi:[0,1,0]
	v_fma_mix_f32 v12, v8, v89, v12 op_sel_hi:[0,1,0]
	v_fma_mix_f32 v12, v9, v89, v12 op_sel:[0,1,0] op_sel_hi:[0,1,0]
	v_pk_mul_f32 v[48:49], v[6:7], v[84:85]
	v_pk_mul_f32 v[50:51], v[8:9], v[86:87]
	v_add_f32_dpp v12, v12, v12 row_ror:1 row_mask:0xf bank_mask:0xf bound_ctrl:1
	v_fma_mix_f32 v100, v6, v38, v180 op_sel_hi:[0,1,0]
	v_fma_mix_f32 v100, v7, v38, v100 op_sel:[0,1,0] op_sel_hi:[0,1,0]
	v_add_f32_dpp v12, v12, v12 row_ror:2 row_mask:0xf bank_mask:0xf bound_ctrl:1
	v_pk_fma_f32 v[48:49], v[96:97], v[68:69], v[48:49] op_sel_hi:[1,0,1]
	v_pk_fma_f32 v[50:51], v[98:99], v[68:69], v[50:51] op_sel_hi:[1,0,1]
	v_add_f32_dpp v12, v12, v12 row_ror:4 row_mask:0xf bank_mask:0xf bound_ctrl:1
	v_fma_mix_f32 v100, v8, v39, v100 op_sel_hi:[0,1,0]
	v_fma_mix_f32 v100, v9, v39, v100 op_sel:[0,1,0] op_sel_hi:[0,1,0]
	v_add_f32_dpp v12, v12, v12 row_ror:8 row_mask:0xf bank_mask:0xf bound_ctrl:1
	v_pk_fma_f32 v[6:7], v[92:93], v[12:13], v[48:49] op_sel_hi:[1,0,1] neg_lo:[1,0,0] neg_hi:[1,0,0]
	v_pk_fma_f32 v[8:9], v[94:95], v[12:13], v[50:51] op_sel_hi:[1,0,1] neg_lo:[1,0,0] neg_hi:[1,0,0]
	ds_read_b128 v[20:23], v10 offset:45312
	ds_read_b128 v[16:19], v10 offset:45056
	ds_read_b128 v[28:31], v10 offset:45824
	ds_read_b128 v[24:27], v10 offset:45568
	s_waitcnt lgkmcnt(5)
	v_fma_mix_f32 v12, v6, v110, v180 op_sel_hi:[0,1,0]
	v_fma_mix_f32 v12, v7, v110, v12 op_sel:[0,1,0] op_sel_hi:[0,1,0]
	v_fma_mix_f32 v12, v8, v111, v12 op_sel_hi:[0,1,0]
	v_fma_mix_f32 v12, v9, v111, v12 op_sel:[0,1,0] op_sel_hi:[0,1,0]
	v_pk_mul_f32 v[48:49], v[6:7], v[106:107]
	v_pk_mul_f32 v[50:51], v[8:9], v[108:109]
	v_add_f32_dpp v12, v12, v12 row_ror:1 row_mask:0xf bank_mask:0xf bound_ctrl:1
	v_fma_mix_f32 v101, v6, v90, v180 op_sel_hi:[0,1,0]
	v_fma_mix_f32 v101, v7, v90, v101 op_sel:[0,1,0] op_sel_hi:[0,1,0]
	v_add_f32_dpp v12, v12, v12 row_ror:2 row_mask:0xf bank_mask:0xf bound_ctrl:1
	v_pk_fma_f32 v[48:49], v[118:119], v[68:69], v[48:49] op_sel:[0,1,0]
	v_pk_fma_f32 v[50:51], v[120:121], v[68:69], v[50:51] op_sel:[0,1,0]
	v_add_f32_dpp v12, v12, v12 row_ror:4 row_mask:0xf bank_mask:0xf bound_ctrl:1
	v_fma_mix_f32 v101, v8, v91, v101 op_sel_hi:[0,1,0]
	v_fma_mix_f32 v101, v9, v91, v101 op_sel:[0,1,0] op_sel_hi:[0,1,0]
	v_add_f32_dpp v12, v12, v12 row_ror:8 row_mask:0xf bank_mask:0xf bound_ctrl:1
	v_pk_fma_f32 v[6:7], v[114:115], v[12:13], v[48:49] op_sel_hi:[1,0,1] neg_lo:[1,0,0] neg_hi:[1,0,0]
	v_pk_fma_f32 v[8:9], v[116:117], v[12:13], v[50:51] op_sel_hi:[1,0,1] neg_lo:[1,0,0] neg_hi:[1,0,0]
	ds_read_b128 v[36:39], v10 offset:46336
	ds_read_b128 v[32:35], v10 offset:46080
	ds_read_b128 v[44:47], v10 offset:46848
	ds_read_b128 v[40:43], v10 offset:46592
	s_waitcnt lgkmcnt(4)
	v_fma_mix_f32 v12, v6, v20, v180 op_sel_hi:[0,1,0]
	v_fma_mix_f32 v12, v7, v20, v12 op_sel:[0,1,0] op_sel_hi:[0,1,0]
	v_fma_mix_f32 v12, v8, v21, v12 op_sel_hi:[0,1,0]
	v_fma_mix_f32 v12, v9, v21, v12 op_sel:[0,1,0] op_sel_hi:[0,1,0]
	v_pk_mul_f32 v[48:49], v[6:7], v[16:17]
	v_pk_mul_f32 v[50:51], v[8:9], v[18:19]
	v_add_f32_dpp v12, v12, v12 row_ror:1 row_mask:0xf bank_mask:0xf bound_ctrl:1
	v_fma_mix_f32 v102, v6, v112, v180 op_sel_hi:[0,1,0]
	v_fma_mix_f32 v102, v7, v112, v102 op_sel:[0,1,0] op_sel_hi:[0,1,0]
	v_add_f32_dpp v12, v12, v12 row_ror:2 row_mask:0xf bank_mask:0xf bound_ctrl:1
	v_pk_fma_f32 v[48:49], v[28:29], v[70:71], v[48:49] op_sel_hi:[1,0,1]
	v_pk_fma_f32 v[50:51], v[30:31], v[70:71], v[50:51] op_sel_hi:[1,0,1]
	v_add_f32_dpp v12, v12, v12 row_ror:4 row_mask:0xf bank_mask:0xf bound_ctrl:1
	v_fma_mix_f32 v102, v8, v113, v102 op_sel_hi:[0,1,0]
	v_fma_mix_f32 v102, v9, v113, v102 op_sel:[0,1,0] op_sel_hi:[0,1,0]
	v_add_f32_dpp v12, v12, v12 row_ror:8 row_mask:0xf bank_mask:0xf bound_ctrl:1
	v_pk_fma_f32 v[6:7], v[24:25], v[12:13], v[48:49] op_sel_hi:[1,0,1] neg_lo:[1,0,0] neg_hi:[1,0,0]
	v_pk_fma_f32 v[8:9], v[26:27], v[12:13], v[50:51] op_sel_hi:[1,0,1] neg_lo:[1,0,0] neg_hi:[1,0,0]
	ds_read_b128 v[88:91], v10 offset:47360
	ds_read_b128 v[84:87], v10 offset:47104
	ds_read_b128 v[96:99], v10 offset:47872
	ds_read_b128 v[92:95], v10 offset:47616
	s_waitcnt lgkmcnt(4)
	v_fma_mix_f32 v12, v6, v36, v180 op_sel_hi:[0,1,0]
	v_fma_mix_f32 v12, v7, v36, v12 op_sel:[0,1,0] op_sel_hi:[0,1,0]
	v_fma_mix_f32 v12, v8, v37, v12 op_sel_hi:[0,1,0]
	v_fma_mix_f32 v12, v9, v37, v12 op_sel:[0,1,0] op_sel_hi:[0,1,0]
	v_pk_mul_f32 v[48:49], v[6:7], v[32:33]
	v_pk_mul_f32 v[50:51], v[8:9], v[34:35]
	v_add_f32_dpp v12, v12, v12 row_ror:1 row_mask:0xf bank_mask:0xf bound_ctrl:1
	v_fma_mix_f32 v103, v6, v22, v180 op_sel_hi:[0,1,0]
	v_fma_mix_f32 v103, v7, v22, v103 op_sel:[0,1,0] op_sel_hi:[0,1,0]
	v_add_f32_dpp v12, v12, v12 row_ror:2 row_mask:0xf bank_mask:0xf bound_ctrl:1
	v_pk_fma_f32 v[48:49], v[44:45], v[70:71], v[48:49] op_sel:[0,1,0]
	v_pk_fma_f32 v[50:51], v[46:47], v[70:71], v[50:51] op_sel:[0,1,0]
	v_add_f32_dpp v12, v12, v12 row_ror:4 row_mask:0xf bank_mask:0xf bound_ctrl:1
	v_fma_mix_f32 v103, v8, v23, v103 op_sel_hi:[0,1,0]
	v_fma_mix_f32 v103, v9, v23, v103 op_sel:[0,1,0] op_sel_hi:[0,1,0]
	v_add_f32_dpp v12, v12, v12 row_ror:8 row_mask:0xf bank_mask:0xf bound_ctrl:1
	v_pk_fma_f32 v[6:7], v[40:41], v[12:13], v[48:49] op_sel_hi:[1,0,1] neg_lo:[1,0,0] neg_hi:[1,0,0]
	v_pk_fma_f32 v[8:9], v[42:43], v[12:13], v[50:51] op_sel_hi:[1,0,1] neg_lo:[1,0,0] neg_hi:[1,0,0]
	ds_read_b128 v[110:113], v10 offset:48384
	ds_read_b128 v[106:109], v10 offset:48128
	ds_read_b128 v[118:121], v10 offset:48896
	ds_read_b128 v[114:117], v10 offset:48640
	ds_read_b128 v[66:69], v11 offset:3072
	s_waitcnt lgkmcnt(5)
	v_fma_mix_f32 v12, v6, v88, v180 op_sel_hi:[0,1,0]
	v_fma_mix_f32 v12, v7, v88, v12 op_sel:[0,1,0] op_sel_hi:[0,1,0]
	v_fma_mix_f32 v12, v8, v89, v12 op_sel_hi:[0,1,0]
	v_fma_mix_f32 v12, v9, v89, v12 op_sel:[0,1,0] op_sel_hi:[0,1,0]
	v_pk_mul_f32 v[48:49], v[6:7], v[84:85]
	v_pk_mul_f32 v[50:51], v[8:9], v[86:87]
	v_add_f32_dpp v12, v12, v12 row_ror:1 row_mask:0xf bank_mask:0xf bound_ctrl:1
	v_fma_mix_f32 v104, v6, v38, v180 op_sel_hi:[0,1,0]
	v_fma_mix_f32 v104, v7, v38, v104 op_sel:[0,1,0] op_sel_hi:[0,1,0]
	v_add_f32_dpp v12, v12, v12 row_ror:2 row_mask:0xf bank_mask:0xf bound_ctrl:1
	v_pk_fma_f32 v[48:49], v[96:97], v[72:73], v[48:49] op_sel_hi:[1,0,1]
	v_pk_fma_f32 v[50:51], v[98:99], v[72:73], v[50:51] op_sel_hi:[1,0,1]
	v_add_f32_dpp v12, v12, v12 row_ror:4 row_mask:0xf bank_mask:0xf bound_ctrl:1
	v_fma_mix_f32 v104, v8, v39, v104 op_sel_hi:[0,1,0]
	v_fma_mix_f32 v104, v9, v39, v104 op_sel:[0,1,0] op_sel_hi:[0,1,0]
	v_add_f32_dpp v12, v12, v12 row_ror:8 row_mask:0xf bank_mask:0xf bound_ctrl:1
	v_pk_fma_f32 v[6:7], v[92:93], v[12:13], v[48:49] op_sel_hi:[1,0,1] neg_lo:[1,0,0] neg_hi:[1,0,0]
	v_pk_fma_f32 v[8:9], v[94:95], v[12:13], v[50:51] op_sel_hi:[1,0,1] neg_lo:[1,0,0] neg_hi:[1,0,0]
	ds_read_b128 v[20:23], v10 offset:49408
	ds_read_b128 v[16:19], v10 offset:49152
	ds_read_b128 v[28:31], v10 offset:49920
	ds_read_b128 v[24:27], v10 offset:49664
	s_waitcnt lgkmcnt(5)
	v_fma_mix_f32 v12, v6, v110, v180 op_sel_hi:[0,1,0]
	v_fma_mix_f32 v12, v7, v110, v12 op_sel:[0,1,0] op_sel_hi:[0,1,0]
	v_fma_mix_f32 v12, v8, v111, v12 op_sel_hi:[0,1,0]
	v_fma_mix_f32 v12, v9, v111, v12 op_sel:[0,1,0] op_sel_hi:[0,1,0]
	v_pk_mul_f32 v[48:49], v[6:7], v[106:107]
	v_pk_mul_f32 v[50:51], v[8:9], v[108:109]
	v_add_f32_dpp v12, v12, v12 row_ror:1 row_mask:0xf bank_mask:0xf bound_ctrl:1
	v_fma_mix_f32 v105, v6, v90, v180 op_sel_hi:[0,1,0]
	v_fma_mix_f32 v105, v7, v90, v105 op_sel:[0,1,0] op_sel_hi:[0,1,0]
	v_add_f32_dpp v12, v12, v12 row_ror:2 row_mask:0xf bank_mask:0xf bound_ctrl:1
	v_pk_fma_f32 v[48:49], v[118:119], v[72:73], v[48:49] op_sel:[0,1,0]
	v_pk_fma_f32 v[50:51], v[120:121], v[72:73], v[50:51] op_sel:[0,1,0]
	v_add_f32_dpp v12, v12, v12 row_ror:4 row_mask:0xf bank_mask:0xf bound_ctrl:1
	v_fma_mix_f32 v105, v8, v91, v105 op_sel_hi:[0,1,0]
	v_fma_mix_f32 v105, v9, v91, v105 op_sel:[0,1,0] op_sel_hi:[0,1,0]
	v_add_f32_dpp v12, v12, v12 row_ror:8 row_mask:0xf bank_mask:0xf bound_ctrl:1
	v_pk_fma_f32 v[6:7], v[114:115], v[12:13], v[48:49] op_sel_hi:[1,0,1] neg_lo:[1,0,0] neg_hi:[1,0,0]
	v_pk_fma_f32 v[8:9], v[116:117], v[12:13], v[50:51] op_sel_hi:[1,0,1] neg_lo:[1,0,0] neg_hi:[1,0,0]
	ds_read_b128 v[36:39], v10 offset:50432
	ds_read_b128 v[32:35], v10 offset:50176
	ds_read_b128 v[44:47], v10 offset:50944
	ds_read_b128 v[40:43], v10 offset:50688
	s_waitcnt lgkmcnt(4)
	v_fma_mix_f32 v12, v6, v20, v180 op_sel_hi:[0,1,0]
	v_fma_mix_f32 v12, v7, v20, v12 op_sel:[0,1,0] op_sel_hi:[0,1,0]
	v_fma_mix_f32 v12, v8, v21, v12 op_sel_hi:[0,1,0]
	v_fma_mix_f32 v12, v9, v21, v12 op_sel:[0,1,0] op_sel_hi:[0,1,0]
	v_pk_mul_f32 v[48:49], v[6:7], v[16:17]
	v_pk_mul_f32 v[50:51], v[8:9], v[18:19]
	v_add_f32_dpp v12, v12, v12 row_ror:1 row_mask:0xf bank_mask:0xf bound_ctrl:1
	v_fma_mix_f32 v61, v6, v112, v180 op_sel_hi:[0,1,0]
	v_fma_mix_f32 v61, v7, v112, v61 op_sel:[0,1,0] op_sel_hi:[0,1,0]
	v_add_f32_dpp v12, v12, v12 row_ror:2 row_mask:0xf bank_mask:0xf bound_ctrl:1
	v_pk_fma_f32 v[48:49], v[28:29], v[66:67], v[48:49] op_sel_hi:[1,0,1]
	v_pk_fma_f32 v[50:51], v[30:31], v[66:67], v[50:51] op_sel_hi:[1,0,1]
	v_add_f32_dpp v12, v12, v12 row_ror:4 row_mask:0xf bank_mask:0xf bound_ctrl:1
	v_fma_mix_f32 v61, v8, v113, v61 op_sel_hi:[0,1,0]
	v_fma_mix_f32 v61, v9, v113, v61 op_sel:[0,1,0] op_sel_hi:[0,1,0]
	v_add_f32_dpp v12, v12, v12 row_ror:8 row_mask:0xf bank_mask:0xf bound_ctrl:1
	v_pk_fma_f32 v[6:7], v[24:25], v[12:13], v[48:49] op_sel_hi:[1,0,1] neg_lo:[1,0,0] neg_hi:[1,0,0]
	v_pk_fma_f32 v[8:9], v[26:27], v[12:13], v[50:51] op_sel_hi:[1,0,1] neg_lo:[1,0,0] neg_hi:[1,0,0]
	ds_read_b128 v[88:91], v10 offset:51456
	ds_read_b128 v[84:87], v10 offset:51200
	ds_read_b128 v[96:99], v10 offset:51968
	ds_read_b128 v[92:95], v10 offset:51712
	v_add_f32_dpp v83, v83, v83 row_ror:8 row_mask:0xf bank_mask:0xc
	v_add_f32_dpp v83, v52, v52 row_ror:8 row_mask:0xf bank_mask:0x3
	v_add_f32_dpp v100, v100, v100 row_ror:8 row_mask:0xf bank_mask:0xc
	v_add_f32_dpp v100, v53, v53 row_ror:8 row_mask:0xf bank_mask:0x3
	v_add_f32_dpp v101, v101, v101 row_ror:8 row_mask:0xf bank_mask:0xc
	v_add_f32_dpp v101, v54, v54 row_ror:8 row_mask:0xf bank_mask:0x3
	v_add_f32_dpp v102, v102, v102 row_ror:8 row_mask:0xf bank_mask:0xc
	v_add_f32_dpp v102, v55, v55 row_ror:8 row_mask:0xf bank_mask:0x3
	v_add_f32_dpp v103, v103, v103 row_ror:8 row_mask:0xf bank_mask:0xc
	v_add_f32_dpp v103, v56, v56 row_ror:8 row_mask:0xf bank_mask:0x3
	v_add_f32_dpp v104, v104, v104 row_ror:8 row_mask:0xf bank_mask:0xc
	v_add_f32_dpp v104, v57, v57 row_ror:8 row_mask:0xf bank_mask:0x3
	v_add_f32_dpp v105, v105, v105 row_ror:8 row_mask:0xf bank_mask:0xc
	v_add_f32_dpp v105, v81, v81 row_ror:8 row_mask:0xf bank_mask:0x3
	v_add_f32_dpp v61, v61, v61 row_ror:8 row_mask:0xf bank_mask:0xc
	v_add_f32_dpp v61, v82, v82 row_ror:8 row_mask:0xf bank_mask:0x3
	v_add_f32_dpp v103, v103, v103 row_ror:4 row_mask:0xf bank_mask:0xa
	v_add_f32_dpp v103, v83, v83 row_ror:12 row_mask:0xf bank_mask:0x5
	v_add_f32_dpp v104, v104, v104 row_ror:4 row_mask:0xf bank_mask:0xa
	v_add_f32_dpp v104, v100, v100 row_ror:12 row_mask:0xf bank_mask:0x5
	v_add_f32_dpp v105, v105, v105 row_ror:4 row_mask:0xf bank_mask:0xa
	v_add_f32_dpp v105, v101, v101 row_ror:12 row_mask:0xf bank_mask:0x5
	v_add_f32_dpp v61, v61, v61 row_ror:4 row_mask:0xf bank_mask:0xa
	v_add_f32_dpp v61, v102, v102 row_ror:12 row_mask:0xf bank_mask:0x5
	v_cndmask_b32_e64 v62, v105, v103, s[38:39]
	v_cndmask_b32_e64 v63, v103, v105, s[38:39]
	v_cndmask_b32_e64 v64, v61, v104, s[38:39]
	v_cndmask_b32_e64 v65, v104, v61, s[38:39]
	v_add_f32_dpp v62, v63, v62 quad_perm:[2,3,0,1] row_mask:0xf bank_mask:0xf bound_ctrl:1
	s_nop 0
	v_add_f32_dpp v63, v65, v64 quad_perm:[2,3,0,1] row_mask:0xf bank_mask:0xf bound_ctrl:1
	v_cndmask_b32_e64 v65, v63, v62, s[40:41]
	v_cndmask_b32_e64 v62, v62, v63, s[40:41]
	s_nop 1
	v_add_f32_dpp v62, v62, v65 quad_perm:[1,0,3,2] row_mask:0xf bank_mask:0xf bound_ctrl:1
	v_cvt_pk_bf16_f32 v62, v62, v62
	global_store_short v[2:3], v62, off
	v_lshl_add_u64 v[2:3], v[2:3], 0, s[84:85]
	s_waitcnt lgkmcnt(4)
	v_fma_mix_f32 v12, v6, v36, v180 op_sel_hi:[0,1,0]
	v_fma_mix_f32 v12, v7, v36, v12 op_sel:[0,1,0] op_sel_hi:[0,1,0]
	v_fma_mix_f32 v12, v8, v37, v12 op_sel_hi:[0,1,0]
	v_fma_mix_f32 v12, v9, v37, v12 op_sel:[0,1,0] op_sel_hi:[0,1,0]
	v_pk_mul_f32 v[48:49], v[6:7], v[32:33]
	v_pk_mul_f32 v[50:51], v[8:9], v[34:35]
	v_add_f32_dpp v12, v12, v12 row_ror:1 row_mask:0xf bank_mask:0xf bound_ctrl:1
	v_fma_mix_f32 v52, v6, v22, v180 op_sel_hi:[0,1,0]
	v_fma_mix_f32 v52, v7, v22, v52 op_sel:[0,1,0] op_sel_hi:[0,1,0]
	v_add_f32_dpp v12, v12, v12 row_ror:2 row_mask:0xf bank_mask:0xf bound_ctrl:1
	v_pk_fma_f32 v[48:49], v[44:45], v[66:67], v[48:49] op_sel:[0,1,0]
	v_pk_fma_f32 v[50:51], v[46:47], v[66:67], v[50:51] op_sel:[0,1,0]
	v_add_f32_dpp v12, v12, v12 row_ror:4 row_mask:0xf bank_mask:0xf bound_ctrl:1
	v_fma_mix_f32 v52, v8, v23, v52 op_sel_hi:[0,1,0]
	v_fma_mix_f32 v52, v9, v23, v52 op_sel:[0,1,0] op_sel_hi:[0,1,0]
	v_add_f32_dpp v12, v12, v12 row_ror:8 row_mask:0xf bank_mask:0xf bound_ctrl:1
	v_pk_fma_f32 v[6:7], v[40:41], v[12:13], v[48:49] op_sel_hi:[1,0,1] neg_lo:[1,0,0] neg_hi:[1,0,0]
	v_pk_fma_f32 v[8:9], v[42:43], v[12:13], v[50:51] op_sel_hi:[1,0,1] neg_lo:[1,0,0] neg_hi:[1,0,0]
	ds_read_b128 v[110:113], v10 offset:52480
	ds_read_b128 v[106:109], v10 offset:52224
	ds_read_b128 v[118:121], v10 offset:52992
	ds_read_b128 v[114:117], v10 offset:52736
	ds_read_b128 v[70:73], v11 offset:3328
	s_waitcnt lgkmcnt(5)
	v_fma_mix_f32 v12, v6, v88, v180 op_sel_hi:[0,1,0]
	v_fma_mix_f32 v12, v7, v88, v12 op_sel:[0,1,0] op_sel_hi:[0,1,0]
	v_fma_mix_f32 v12, v8, v89, v12 op_sel_hi:[0,1,0]
	v_fma_mix_f32 v12, v9, v89, v12 op_sel:[0,1,0] op_sel_hi:[0,1,0]
	v_pk_mul_f32 v[48:49], v[6:7], v[84:85]
	v_pk_mul_f32 v[50:51], v[8:9], v[86:87]
	v_add_f32_dpp v12, v12, v12 row_ror:1 row_mask:0xf bank_mask:0xf bound_ctrl:1
	v_fma_mix_f32 v53, v6, v38, v180 op_sel_hi:[0,1,0]
	v_fma_mix_f32 v53, v7, v38, v53 op_sel:[0,1,0] op_sel_hi:[0,1,0]
	v_add_f32_dpp v12, v12, v12 row_ror:2 row_mask:0xf bank_mask:0xf bound_ctrl:1
	v_pk_fma_f32 v[48:49], v[96:97], v[68:69], v[48:49] op_sel_hi:[1,0,1]
	v_pk_fma_f32 v[50:51], v[98:99], v[68:69], v[50:51] op_sel_hi:[1,0,1]
	v_add_f32_dpp v12, v12, v12 row_ror:4 row_mask:0xf bank_mask:0xf bound_ctrl:1
	v_fma_mix_f32 v53, v8, v39, v53 op_sel_hi:[0,1,0]
	v_fma_mix_f32 v53, v9, v39, v53 op_sel:[0,1,0] op_sel_hi:[0,1,0]
	v_add_f32_dpp v12, v12, v12 row_ror:8 row_mask:0xf bank_mask:0xf bound_ctrl:1
	v_pk_fma_f32 v[6:7], v[92:93], v[12:13], v[48:49] op_sel_hi:[1,0,1] neg_lo:[1,0,0] neg_hi:[1,0,0]
	v_pk_fma_f32 v[8:9], v[94:95], v[12:13], v[50:51] op_sel_hi:[1,0,1] neg_lo:[1,0,0] neg_hi:[1,0,0]
	ds_read_b128 v[20:23], v10 offset:53504
	ds_read_b128 v[16:19], v10 offset:53248
	ds_read_b128 v[28:31], v10 offset:54016
	ds_read_b128 v[24:27], v10 offset:53760
	s_waitcnt lgkmcnt(5)
	v_fma_mix_f32 v12, v6, v110, v180 op_sel_hi:[0,1,0]
	v_fma_mix_f32 v12, v7, v110, v12 op_sel:[0,1,0] op_sel_hi:[0,1,0]
	v_fma_mix_f32 v12, v8, v111, v12 op_sel_hi:[0,1,0]
	v_fma_mix_f32 v12, v9, v111, v12 op_sel:[0,1,0] op_sel_hi:[0,1,0]
	v_pk_mul_f32 v[48:49], v[6:7], v[106:107]
	v_pk_mul_f32 v[50:51], v[8:9], v[108:109]
	v_add_f32_dpp v12, v12, v12 row_ror:1 row_mask:0xf bank_mask:0xf bound_ctrl:1
	v_fma_mix_f32 v54, v6, v90, v180 op_sel_hi:[0,1,0]
	v_fma_mix_f32 v54, v7, v90, v54 op_sel:[0,1,0] op_sel_hi:[0,1,0]
	v_add_f32_dpp v12, v12, v12 row_ror:2 row_mask:0xf bank_mask:0xf bound_ctrl:1
	v_pk_fma_f32 v[48:49], v[118:119], v[68:69], v[48:49] op_sel:[0,1,0]
	v_pk_fma_f32 v[50:51], v[120:121], v[68:69], v[50:51] op_sel:[0,1,0]
	v_add_f32_dpp v12, v12, v12 row_ror:4 row_mask:0xf bank_mask:0xf bound_ctrl:1
	v_fma_mix_f32 v54, v8, v91, v54 op_sel_hi:[0,1,0]
	v_fma_mix_f32 v54, v9, v91, v54 op_sel:[0,1,0] op_sel_hi:[0,1,0]
	v_add_f32_dpp v12, v12, v12 row_ror:8 row_mask:0xf bank_mask:0xf bound_ctrl:1
	v_pk_fma_f32 v[6:7], v[114:115], v[12:13], v[48:49] op_sel_hi:[1,0,1] neg_lo:[1,0,0] neg_hi:[1,0,0]
	v_pk_fma_f32 v[8:9], v[116:117], v[12:13], v[50:51] op_sel_hi:[1,0,1] neg_lo:[1,0,0] neg_hi:[1,0,0]
	ds_read_b128 v[36:39], v10 offset:54528
	ds_read_b128 v[32:35], v10 offset:54272
	ds_read_b128 v[44:47], v10 offset:55040
	ds_read_b128 v[40:43], v10 offset:54784
	s_waitcnt lgkmcnt(4)
	v_fma_mix_f32 v12, v6, v20, v180 op_sel_hi:[0,1,0]
	v_fma_mix_f32 v12, v7, v20, v12 op_sel:[0,1,0] op_sel_hi:[0,1,0]
	v_fma_mix_f32 v12, v8, v21, v12 op_sel_hi:[0,1,0]
	v_fma_mix_f32 v12, v9, v21, v12 op_sel:[0,1,0] op_sel_hi:[0,1,0]
	v_pk_mul_f32 v[48:49], v[6:7], v[16:17]
	v_pk_mul_f32 v[50:51], v[8:9], v[18:19]
	v_add_f32_dpp v12, v12, v12 row_ror:1 row_mask:0xf bank_mask:0xf bound_ctrl:1
	v_fma_mix_f32 v55, v6, v112, v180 op_sel_hi:[0,1,0]
	v_fma_mix_f32 v55, v7, v112, v55 op_sel:[0,1,0] op_sel_hi:[0,1,0]
	v_add_f32_dpp v12, v12, v12 row_ror:2 row_mask:0xf bank_mask:0xf bound_ctrl:1
	v_pk_fma_f32 v[48:49], v[28:29], v[70:71], v[48:49] op_sel_hi:[1,0,1]
	v_pk_fma_f32 v[50:51], v[30:31], v[70:71], v[50:51] op_sel_hi:[1,0,1]
	v_add_f32_dpp v12, v12, v12 row_ror:4 row_mask:0xf bank_mask:0xf bound_ctrl:1
	v_fma_mix_f32 v55, v8, v113, v55 op_sel_hi:[0,1,0]
	v_fma_mix_f32 v55, v9, v113, v55 op_sel:[0,1,0] op_sel_hi:[0,1,0]
	v_add_f32_dpp v12, v12, v12 row_ror:8 row_mask:0xf bank_mask:0xf bound_ctrl:1
	v_pk_fma_f32 v[6:7], v[24:25], v[12:13], v[48:49] op_sel_hi:[1,0,1] neg_lo:[1,0,0] neg_hi:[1,0,0]
	v_pk_fma_f32 v[8:9], v[26:27], v[12:13], v[50:51] op_sel_hi:[1,0,1] neg_lo:[1,0,0] neg_hi:[1,0,0]
	ds_read_b128 v[88:91], v10 offset:55552
	ds_read_b128 v[84:87], v10 offset:55296
	ds_read_b128 v[96:99], v10 offset:56064
	ds_read_b128 v[92:95], v10 offset:55808
	s_waitcnt lgkmcnt(4)
	v_fma_mix_f32 v12, v6, v36, v180 op_sel_hi:[0,1,0]
	v_fma_mix_f32 v12, v7, v36, v12 op_sel:[0,1,0] op_sel_hi:[0,1,0]
	v_fma_mix_f32 v12, v8, v37, v12 op_sel_hi:[0,1,0]
	v_fma_mix_f32 v12, v9, v37, v12 op_sel:[0,1,0] op_sel_hi:[0,1,0]
	v_pk_mul_f32 v[48:49], v[6:7], v[32:33]
	v_pk_mul_f32 v[50:51], v[8:9], v[34:35]
	v_add_f32_dpp v12, v12, v12 row_ror:1 row_mask:0xf bank_mask:0xf bound_ctrl:1
	v_fma_mix_f32 v56, v6, v22, v180 op_sel_hi:[0,1,0]
	v_fma_mix_f32 v56, v7, v22, v56 op_sel:[0,1,0] op_sel_hi:[0,1,0]
	v_add_f32_dpp v12, v12, v12 row_ror:2 row_mask:0xf bank_mask:0xf bound_ctrl:1
	v_pk_fma_f32 v[48:49], v[44:45], v[70:71], v[48:49] op_sel:[0,1,0]
	v_pk_fma_f32 v[50:51], v[46:47], v[70:71], v[50:51] op_sel:[0,1,0]
	v_add_f32_dpp v12, v12, v12 row_ror:4 row_mask:0xf bank_mask:0xf bound_ctrl:1
	v_fma_mix_f32 v56, v8, v23, v56 op_sel_hi:[0,1,0]
	v_fma_mix_f32 v56, v9, v23, v56 op_sel:[0,1,0] op_sel_hi:[0,1,0]
	v_add_f32_dpp v12, v12, v12 row_ror:8 row_mask:0xf bank_mask:0xf bound_ctrl:1
	v_pk_fma_f32 v[6:7], v[40:41], v[12:13], v[48:49] op_sel_hi:[1,0,1] neg_lo:[1,0,0] neg_hi:[1,0,0]
	v_pk_fma_f32 v[8:9], v[42:43], v[12:13], v[50:51] op_sel_hi:[1,0,1] neg_lo:[1,0,0] neg_hi:[1,0,0]
	ds_read_b128 v[110:113], v10 offset:56576
	ds_read_b128 v[106:109], v10 offset:56320
	ds_read_b128 v[118:121], v10 offset:57088
	ds_read_b128 v[114:117], v10 offset:56832
	ds_read_b128 v[66:69], v11 offset:3584
	s_waitcnt lgkmcnt(5)
	v_fma_mix_f32 v12, v6, v88, v180 op_sel_hi:[0,1,0]
	v_fma_mix_f32 v12, v7, v88, v12 op_sel:[0,1,0] op_sel_hi:[0,1,0]
	v_fma_mix_f32 v12, v8, v89, v12 op_sel_hi:[0,1,0]
	v_fma_mix_f32 v12, v9, v89, v12 op_sel:[0,1,0] op_sel_hi:[0,1,0]
	v_pk_mul_f32 v[48:49], v[6:7], v[84:85]
	v_pk_mul_f32 v[50:51], v[8:9], v[86:87]
	v_add_f32_dpp v12, v12, v12 row_ror:1 row_mask:0xf bank_mask:0xf bound_ctrl:1
	v_fma_mix_f32 v57, v6, v38, v180 op_sel_hi:[0,1,0]
	v_fma_mix_f32 v57, v7, v38, v57 op_sel:[0,1,0] op_sel_hi:[0,1,0]
	v_add_f32_dpp v12, v12, v12 row_ror:2 row_mask:0xf bank_mask:0xf bound_ctrl:1
	v_pk_fma_f32 v[48:49], v[96:97], v[72:73], v[48:49] op_sel_hi:[1,0,1]
	v_pk_fma_f32 v[50:51], v[98:99], v[72:73], v[50:51] op_sel_hi:[1,0,1]
	v_add_f32_dpp v12, v12, v12 row_ror:4 row_mask:0xf bank_mask:0xf bound_ctrl:1
	v_fma_mix_f32 v57, v8, v39, v57 op_sel_hi:[0,1,0]
	v_fma_mix_f32 v57, v9, v39, v57 op_sel:[0,1,0] op_sel_hi:[0,1,0]
	v_add_f32_dpp v12, v12, v12 row_ror:8 row_mask:0xf bank_mask:0xf bound_ctrl:1
	v_pk_fma_f32 v[6:7], v[92:93], v[12:13], v[48:49] op_sel_hi:[1,0,1] neg_lo:[1,0,0] neg_hi:[1,0,0]
	v_pk_fma_f32 v[8:9], v[94:95], v[12:13], v[50:51] op_sel_hi:[1,0,1] neg_lo:[1,0,0] neg_hi:[1,0,0]
	ds_read_b128 v[20:23], v10 offset:57600
	ds_read_b128 v[16:19], v10 offset:57344
	ds_read_b128 v[28:31], v10 offset:58112
	ds_read_b128 v[24:27], v10 offset:57856
	s_waitcnt lgkmcnt(5)
	v_fma_mix_f32 v12, v6, v110, v180 op_sel_hi:[0,1,0]
	v_fma_mix_f32 v12, v7, v110, v12 op_sel:[0,1,0] op_sel_hi:[0,1,0]
	v_fma_mix_f32 v12, v8, v111, v12 op_sel_hi:[0,1,0]
	v_fma_mix_f32 v12, v9, v111, v12 op_sel:[0,1,0] op_sel_hi:[0,1,0]
	v_pk_mul_f32 v[48:49], v[6:7], v[106:107]
	v_pk_mul_f32 v[50:51], v[8:9], v[108:109]
	v_add_f32_dpp v12, v12, v12 row_ror:1 row_mask:0xf bank_mask:0xf bound_ctrl:1
	v_fma_mix_f32 v81, v6, v90, v180 op_sel_hi:[0,1,0]
	v_fma_mix_f32 v81, v7, v90, v81 op_sel:[0,1,0] op_sel_hi:[0,1,0]
	v_add_f32_dpp v12, v12, v12 row_ror:2 row_mask:0xf bank_mask:0xf bound_ctrl:1
	v_pk_fma_f32 v[48:49], v[118:119], v[72:73], v[48:49] op_sel:[0,1,0]
	v_pk_fma_f32 v[50:51], v[120:121], v[72:73], v[50:51] op_sel:[0,1,0]
	v_add_f32_dpp v12, v12, v12 row_ror:4 row_mask:0xf bank_mask:0xf bound_ctrl:1
	v_fma_mix_f32 v81, v8, v91, v81 op_sel_hi:[0,1,0]
	v_fma_mix_f32 v81, v9, v91, v81 op_sel:[0,1,0] op_sel_hi:[0,1,0]
	v_add_f32_dpp v12, v12, v12 row_ror:8 row_mask:0xf bank_mask:0xf bound_ctrl:1
	v_pk_fma_f32 v[6:7], v[114:115], v[12:13], v[48:49] op_sel_hi:[1,0,1] neg_lo:[1,0,0] neg_hi:[1,0,0]
	v_pk_fma_f32 v[8:9], v[116:117], v[12:13], v[50:51] op_sel_hi:[1,0,1] neg_lo:[1,0,0] neg_hi:[1,0,0]
	ds_read_b128 v[36:39], v10 offset:58624
	ds_read_b128 v[32:35], v10 offset:58368
	ds_read_b128 v[44:47], v10 offset:59136
	ds_read_b128 v[40:43], v10 offset:58880
	s_waitcnt lgkmcnt(4)
	v_fma_mix_f32 v12, v6, v20, v180 op_sel_hi:[0,1,0]
	v_fma_mix_f32 v12, v7, v20, v12 op_sel:[0,1,0] op_sel_hi:[0,1,0]
	v_fma_mix_f32 v12, v8, v21, v12 op_sel_hi:[0,1,0]
	v_fma_mix_f32 v12, v9, v21, v12 op_sel:[0,1,0] op_sel_hi:[0,1,0]
	v_pk_mul_f32 v[48:49], v[6:7], v[16:17]
	v_pk_mul_f32 v[50:51], v[8:9], v[18:19]
	v_add_f32_dpp v12, v12, v12 row_ror:1 row_mask:0xf bank_mask:0xf bound_ctrl:1
	v_fma_mix_f32 v82, v6, v112, v180 op_sel_hi:[0,1,0]
	v_fma_mix_f32 v82, v7, v112, v82 op_sel:[0,1,0] op_sel_hi:[0,1,0]
	v_add_f32_dpp v12, v12, v12 row_ror:2 row_mask:0xf bank_mask:0xf bound_ctrl:1
	v_pk_fma_f32 v[48:49], v[28:29], v[66:67], v[48:49] op_sel_hi:[1,0,1]
	v_pk_fma_f32 v[50:51], v[30:31], v[66:67], v[50:51] op_sel_hi:[1,0,1]
	v_add_f32_dpp v12, v12, v12 row_ror:4 row_mask:0xf bank_mask:0xf bound_ctrl:1
	v_fma_mix_f32 v82, v8, v113, v82 op_sel_hi:[0,1,0]
	v_fma_mix_f32 v82, v9, v113, v82 op_sel:[0,1,0] op_sel_hi:[0,1,0]
	v_add_f32_dpp v12, v12, v12 row_ror:8 row_mask:0xf bank_mask:0xf bound_ctrl:1
	v_pk_fma_f32 v[6:7], v[24:25], v[12:13], v[48:49] op_sel_hi:[1,0,1] neg_lo:[1,0,0] neg_hi:[1,0,0]
	v_pk_fma_f32 v[8:9], v[26:27], v[12:13], v[50:51] op_sel_hi:[1,0,1] neg_lo:[1,0,0] neg_hi:[1,0,0]
	ds_read_b128 v[88:91], v10 offset:59648
	ds_read_b128 v[84:87], v10 offset:59392
	ds_read_b128 v[96:99], v10 offset:60160
	ds_read_b128 v[92:95], v10 offset:59904
	s_waitcnt lgkmcnt(4)
	v_fma_mix_f32 v12, v6, v36, v180 op_sel_hi:[0,1,0]
	v_fma_mix_f32 v12, v7, v36, v12 op_sel:[0,1,0] op_sel_hi:[0,1,0]
	v_fma_mix_f32 v12, v8, v37, v12 op_sel_hi:[0,1,0]
	v_fma_mix_f32 v12, v9, v37, v12 op_sel:[0,1,0] op_sel_hi:[0,1,0]
	v_pk_mul_f32 v[48:49], v[6:7], v[32:33]
	v_pk_mul_f32 v[50:51], v[8:9], v[34:35]
	v_add_f32_dpp v12, v12, v12 row_ror:1 row_mask:0xf bank_mask:0xf bound_ctrl:1
	v_fma_mix_f32 v83, v6, v22, v180 op_sel_hi:[0,1,0]
	v_fma_mix_f32 v83, v7, v22, v83 op_sel:[0,1,0] op_sel_hi:[0,1,0]
	v_add_f32_dpp v12, v12, v12 row_ror:2 row_mask:0xf bank_mask:0xf bound_ctrl:1
	v_pk_fma_f32 v[48:49], v[44:45], v[66:67], v[48:49] op_sel:[0,1,0]
	v_pk_fma_f32 v[50:51], v[46:47], v[66:67], v[50:51] op_sel:[0,1,0]
	v_add_f32_dpp v12, v12, v12 row_ror:4 row_mask:0xf bank_mask:0xf bound_ctrl:1
	v_fma_mix_f32 v83, v8, v23, v83 op_sel_hi:[0,1,0]
	v_fma_mix_f32 v83, v9, v23, v83 op_sel:[0,1,0] op_sel_hi:[0,1,0]
	v_add_f32_dpp v12, v12, v12 row_ror:8 row_mask:0xf bank_mask:0xf bound_ctrl:1
	v_pk_fma_f32 v[6:7], v[40:41], v[12:13], v[48:49] op_sel_hi:[1,0,1] neg_lo:[1,0,0] neg_hi:[1,0,0]
	v_pk_fma_f32 v[8:9], v[42:43], v[12:13], v[50:51] op_sel_hi:[1,0,1] neg_lo:[1,0,0] neg_hi:[1,0,0]
	ds_read_b128 v[110:113], v10 offset:60672
	ds_read_b128 v[106:109], v10 offset:60416
	ds_read_b128 v[118:121], v10 offset:61184
	ds_read_b128 v[114:117], v10 offset:60928
	ds_read_b128 v[70:73], v11 offset:3840
	s_waitcnt lgkmcnt(5)
	v_fma_mix_f32 v12, v6, v88, v180 op_sel_hi:[0,1,0]
	v_fma_mix_f32 v12, v7, v88, v12 op_sel:[0,1,0] op_sel_hi:[0,1,0]
	v_fma_mix_f32 v12, v8, v89, v12 op_sel_hi:[0,1,0]
	v_fma_mix_f32 v12, v9, v89, v12 op_sel:[0,1,0] op_sel_hi:[0,1,0]
	v_pk_mul_f32 v[48:49], v[6:7], v[84:85]
	v_pk_mul_f32 v[50:51], v[8:9], v[86:87]
	v_add_f32_dpp v12, v12, v12 row_ror:1 row_mask:0xf bank_mask:0xf bound_ctrl:1
	v_fma_mix_f32 v100, v6, v38, v180 op_sel_hi:[0,1,0]
	v_fma_mix_f32 v100, v7, v38, v100 op_sel:[0,1,0] op_sel_hi:[0,1,0]
	v_add_f32_dpp v12, v12, v12 row_ror:2 row_mask:0xf bank_mask:0xf bound_ctrl:1
	v_pk_fma_f32 v[48:49], v[96:97], v[68:69], v[48:49] op_sel_hi:[1,0,1]
	v_pk_fma_f32 v[50:51], v[98:99], v[68:69], v[50:51] op_sel_hi:[1,0,1]
	v_add_f32_dpp v12, v12, v12 row_ror:4 row_mask:0xf bank_mask:0xf bound_ctrl:1
	v_fma_mix_f32 v100, v8, v39, v100 op_sel_hi:[0,1,0]
	v_fma_mix_f32 v100, v9, v39, v100 op_sel:[0,1,0] op_sel_hi:[0,1,0]
	v_add_f32_dpp v12, v12, v12 row_ror:8 row_mask:0xf bank_mask:0xf bound_ctrl:1
	v_pk_fma_f32 v[6:7], v[92:93], v[12:13], v[48:49] op_sel_hi:[1,0,1] neg_lo:[1,0,0] neg_hi:[1,0,0]
	v_pk_fma_f32 v[8:9], v[94:95], v[12:13], v[50:51] op_sel_hi:[1,0,1] neg_lo:[1,0,0] neg_hi:[1,0,0]
	ds_read_b128 v[20:23], v10 offset:61696
	ds_read_b128 v[16:19], v10 offset:61440
	ds_read_b128 v[28:31], v10 offset:62208
	ds_read_b128 v[24:27], v10 offset:61952
	s_waitcnt lgkmcnt(5)
	v_fma_mix_f32 v12, v6, v110, v180 op_sel_hi:[0,1,0]
	v_fma_mix_f32 v12, v7, v110, v12 op_sel:[0,1,0] op_sel_hi:[0,1,0]
	v_fma_mix_f32 v12, v8, v111, v12 op_sel_hi:[0,1,0]
	v_fma_mix_f32 v12, v9, v111, v12 op_sel:[0,1,0] op_sel_hi:[0,1,0]
	v_pk_mul_f32 v[48:49], v[6:7], v[106:107]
	v_pk_mul_f32 v[50:51], v[8:9], v[108:109]
	v_add_f32_dpp v12, v12, v12 row_ror:1 row_mask:0xf bank_mask:0xf bound_ctrl:1
	v_fma_mix_f32 v101, v6, v90, v180 op_sel_hi:[0,1,0]
	v_fma_mix_f32 v101, v7, v90, v101 op_sel:[0,1,0] op_sel_hi:[0,1,0]
	v_add_f32_dpp v12, v12, v12 row_ror:2 row_mask:0xf bank_mask:0xf bound_ctrl:1
	v_pk_fma_f32 v[48:49], v[118:119], v[68:69], v[48:49] op_sel:[0,1,0]
	v_pk_fma_f32 v[50:51], v[120:121], v[68:69], v[50:51] op_sel:[0,1,0]
	v_add_f32_dpp v12, v12, v12 row_ror:4 row_mask:0xf bank_mask:0xf bound_ctrl:1
	v_fma_mix_f32 v101, v8, v91, v101 op_sel_hi:[0,1,0]
	v_fma_mix_f32 v101, v9, v91, v101 op_sel:[0,1,0] op_sel_hi:[0,1,0]
	v_add_f32_dpp v12, v12, v12 row_ror:8 row_mask:0xf bank_mask:0xf bound_ctrl:1
	v_pk_fma_f32 v[6:7], v[114:115], v[12:13], v[48:49] op_sel_hi:[1,0,1] neg_lo:[1,0,0] neg_hi:[1,0,0]
	v_pk_fma_f32 v[8:9], v[116:117], v[12:13], v[50:51] op_sel_hi:[1,0,1] neg_lo:[1,0,0] neg_hi:[1,0,0]
	ds_read_b128 v[36:39], v10 offset:62720
	ds_read_b128 v[32:35], v10 offset:62464
	ds_read_b128 v[44:47], v10 offset:63232
	ds_read_b128 v[40:43], v10 offset:62976
	s_waitcnt lgkmcnt(4)
	v_fma_mix_f32 v12, v6, v20, v180 op_sel_hi:[0,1,0]
	v_fma_mix_f32 v12, v7, v20, v12 op_sel:[0,1,0] op_sel_hi:[0,1,0]
	v_fma_mix_f32 v12, v8, v21, v12 op_sel_hi:[0,1,0]
	v_fma_mix_f32 v12, v9, v21, v12 op_sel:[0,1,0] op_sel_hi:[0,1,0]
	v_pk_mul_f32 v[48:49], v[6:7], v[16:17]
	v_pk_mul_f32 v[50:51], v[8:9], v[18:19]
	v_add_f32_dpp v12, v12, v12 row_ror:1 row_mask:0xf bank_mask:0xf bound_ctrl:1
	v_fma_mix_f32 v102, v6, v112, v180 op_sel_hi:[0,1,0]
	v_fma_mix_f32 v102, v7, v112, v102 op_sel:[0,1,0] op_sel_hi:[0,1,0]
	v_add_f32_dpp v12, v12, v12 row_ror:2 row_mask:0xf bank_mask:0xf bound_ctrl:1
	v_pk_fma_f32 v[48:49], v[28:29], v[70:71], v[48:49] op_sel_hi:[1,0,1]
	v_pk_fma_f32 v[50:51], v[30:31], v[70:71], v[50:51] op_sel_hi:[1,0,1]
	v_add_f32_dpp v12, v12, v12 row_ror:4 row_mask:0xf bank_mask:0xf bound_ctrl:1
	v_fma_mix_f32 v102, v8, v113, v102 op_sel_hi:[0,1,0]
	v_fma_mix_f32 v102, v9, v113, v102 op_sel:[0,1,0] op_sel_hi:[0,1,0]
	v_add_f32_dpp v12, v12, v12 row_ror:8 row_mask:0xf bank_mask:0xf bound_ctrl:1
	v_pk_fma_f32 v[6:7], v[24:25], v[12:13], v[48:49] op_sel_hi:[1,0,1] neg_lo:[1,0,0] neg_hi:[1,0,0]
	v_pk_fma_f32 v[8:9], v[26:27], v[12:13], v[50:51] op_sel_hi:[1,0,1] neg_lo:[1,0,0] neg_hi:[1,0,0]
	ds_read_b128 v[88:91], v10 offset:63744
	ds_read_b128 v[84:87], v10 offset:63488
	ds_read_b128 v[96:99], v10 offset:64256
	ds_read_b128 v[92:95], v10 offset:64000
	s_waitcnt lgkmcnt(4)
	v_fma_mix_f32 v12, v6, v36, v180 op_sel_hi:[0,1,0]
	v_fma_mix_f32 v12, v7, v36, v12 op_sel:[0,1,0] op_sel_hi:[0,1,0]
	v_fma_mix_f32 v12, v8, v37, v12 op_sel_hi:[0,1,0]
	v_fma_mix_f32 v12, v9, v37, v12 op_sel:[0,1,0] op_sel_hi:[0,1,0]
	v_pk_mul_f32 v[48:49], v[6:7], v[32:33]
	v_pk_mul_f32 v[50:51], v[8:9], v[34:35]
	v_add_f32_dpp v12, v12, v12 row_ror:1 row_mask:0xf bank_mask:0xf bound_ctrl:1
	v_fma_mix_f32 v103, v6, v22, v180 op_sel_hi:[0,1,0]
	v_fma_mix_f32 v103, v7, v22, v103 op_sel:[0,1,0] op_sel_hi:[0,1,0]
	v_add_f32_dpp v12, v12, v12 row_ror:2 row_mask:0xf bank_mask:0xf bound_ctrl:1
	v_pk_fma_f32 v[48:49], v[44:45], v[70:71], v[48:49] op_sel:[0,1,0]
	v_pk_fma_f32 v[50:51], v[46:47], v[70:71], v[50:51] op_sel:[0,1,0]
	v_add_f32_dpp v12, v12, v12 row_ror:4 row_mask:0xf bank_mask:0xf bound_ctrl:1
	v_fma_mix_f32 v103, v8, v23, v103 op_sel_hi:[0,1,0]
	v_fma_mix_f32 v103, v9, v23, v103 op_sel:[0,1,0] op_sel_hi:[0,1,0]
	v_add_f32_dpp v12, v12, v12 row_ror:8 row_mask:0xf bank_mask:0xf bound_ctrl:1
	v_pk_fma_f32 v[6:7], v[40:41], v[12:13], v[48:49] op_sel_hi:[1,0,1] neg_lo:[1,0,0] neg_hi:[1,0,0]
	v_pk_fma_f32 v[8:9], v[42:43], v[12:13], v[50:51] op_sel_hi:[1,0,1] neg_lo:[1,0,0] neg_hi:[1,0,0]
	ds_read_b128 v[110:113], v10 offset:64768
	ds_read_b128 v[106:109], v10 offset:64512
	ds_read_b128 v[118:121], v10 offset:65280
	ds_read_b128 v[114:117], v10 offset:65024
	s_waitcnt lgkmcnt(4)
	v_fma_mix_f32 v12, v6, v88, v180 op_sel_hi:[0,1,0]
	v_fma_mix_f32 v12, v7, v88, v12 op_sel:[0,1,0] op_sel_hi:[0,1,0]
	v_fma_mix_f32 v12, v8, v89, v12 op_sel_hi:[0,1,0]
	v_fma_mix_f32 v12, v9, v89, v12 op_sel:[0,1,0] op_sel_hi:[0,1,0]
	v_pk_mul_f32 v[48:49], v[6:7], v[84:85]
	v_pk_mul_f32 v[50:51], v[8:9], v[86:87]
	v_add_f32_dpp v12, v12, v12 row_ror:1 row_mask:0xf bank_mask:0xf bound_ctrl:1
	v_fma_mix_f32 v104, v6, v38, v180 op_sel_hi:[0,1,0]
	v_fma_mix_f32 v104, v7, v38, v104 op_sel:[0,1,0] op_sel_hi:[0,1,0]
	v_add_f32_dpp v12, v12, v12 row_ror:2 row_mask:0xf bank_mask:0xf bound_ctrl:1
	v_pk_fma_f32 v[48:49], v[96:97], v[72:73], v[48:49] op_sel_hi:[1,0,1]
	v_pk_fma_f32 v[50:51], v[98:99], v[72:73], v[50:51] op_sel_hi:[1,0,1]
	v_add_f32_dpp v12, v12, v12 row_ror:4 row_mask:0xf bank_mask:0xf bound_ctrl:1
	v_fma_mix_f32 v104, v8, v39, v104 op_sel_hi:[0,1,0]
	v_fma_mix_f32 v104, v9, v39, v104 op_sel:[0,1,0] op_sel_hi:[0,1,0]
	v_add_f32_dpp v12, v12, v12 row_ror:8 row_mask:0xf bank_mask:0xf bound_ctrl:1
	v_pk_fma_f32 v[6:7], v[92:93], v[12:13], v[48:49] op_sel_hi:[1,0,1] neg_lo:[1,0,0] neg_hi:[1,0,0]
	v_pk_fma_f32 v[8:9], v[94:95], v[12:13], v[50:51] op_sel_hi:[1,0,1] neg_lo:[1,0,0] neg_hi:[1,0,0]
	s_waitcnt lgkmcnt(0)
	s_barrier
	v_xor_b32_e32 v10, 0x10000, v10
	v_xor_b32_e32 v11, 0x1000, v11
	ds_read_b128 v[66:69], v11 offset:0
	ds_read_b128 v[20:23], v10 offset:256
	ds_read_b128 v[16:19], v10 offset:0
	ds_read_b128 v[28:31], v10 offset:768
	ds_read_b128 v[24:27], v10 offset:512
	ds_read_b128 v[36:39], v10 offset:1280
	ds_read_b128 v[32:35], v10 offset:1024
	ds_read_b128 v[44:47], v10 offset:1792
	ds_read_b128 v[40:43], v10 offset:1536
	v_fma_mix_f32 v12, v6, v110, v180 op_sel_hi:[0,1,0]
	v_fma_mix_f32 v12, v7, v110, v12 op_sel:[0,1,0] op_sel_hi:[0,1,0]
	v_fma_mix_f32 v12, v8, v111, v12 op_sel_hi:[0,1,0]
	v_fma_mix_f32 v12, v9, v111, v12 op_sel:[0,1,0] op_sel_hi:[0,1,0]
	v_pk_mul_f32 v[48:49], v[6:7], v[106:107]
	v_pk_mul_f32 v[50:51], v[8:9], v[108:109]
	v_add_f32_dpp v12, v12, v12 row_ror:1 row_mask:0xf bank_mask:0xf bound_ctrl:1
	v_fma_mix_f32 v105, v6, v90, v180 op_sel_hi:[0,1,0]
	v_fma_mix_f32 v105, v7, v90, v105 op_sel:[0,1,0] op_sel_hi:[0,1,0]
	v_add_f32_dpp v12, v12, v12 row_ror:2 row_mask:0xf bank_mask:0xf bound_ctrl:1
	v_pk_fma_f32 v[48:49], v[118:119], v[72:73], v[48:49] op_sel:[0,1,0]
	v_pk_fma_f32 v[50:51], v[120:121], v[72:73], v[50:51] op_sel:[0,1,0]
	v_add_f32_dpp v12, v12, v12 row_ror:4 row_mask:0xf bank_mask:0xf bound_ctrl:1
	v_fma_mix_f32 v105, v8, v91, v105 op_sel_hi:[0,1,0]
	v_fma_mix_f32 v105, v9, v91, v105 op_sel:[0,1,0] op_sel_hi:[0,1,0]
	v_add_f32_dpp v12, v12, v12 row_ror:8 row_mask:0xf bank_mask:0xf bound_ctrl:1
	v_pk_fma_f32 v[6:7], v[114:115], v[12:13], v[48:49] op_sel_hi:[1,0,1] neg_lo:[1,0,0] neg_hi:[1,0,0]
	v_pk_fma_f32 v[8:9], v[116:117], v[12:13], v[50:51] op_sel_hi:[1,0,1] neg_lo:[1,0,0] neg_hi:[1,0,0]
	v_fma_mix_f32 v61, v6, v112, v180 op_sel_hi:[0,1,0]
	v_fma_mix_f32 v61, v7, v112, v61 op_sel:[0,1,0] op_sel_hi:[0,1,0]
	v_fma_mix_f32 v61, v8, v113, v61 op_sel_hi:[0,1,0]
	v_fma_mix_f32 v61, v9, v113, v61 op_sel:[0,1,0] op_sel_hi:[0,1,0]
	v_add_f32_dpp v83, v83, v83 row_ror:8 row_mask:0xf bank_mask:0xc
	v_add_f32_dpp v83, v52, v52 row_ror:8 row_mask:0xf bank_mask:0x3
	v_add_f32_dpp v100, v100, v100 row_ror:8 row_mask:0xf bank_mask:0xc
	v_add_f32_dpp v100, v53, v53 row_ror:8 row_mask:0xf bank_mask:0x3
	v_add_f32_dpp v101, v101, v101 row_ror:8 row_mask:0xf bank_mask:0xc
	v_add_f32_dpp v101, v54, v54 row_ror:8 row_mask:0xf bank_mask:0x3
	v_add_f32_dpp v102, v102, v102 row_ror:8 row_mask:0xf bank_mask:0xc
	v_add_f32_dpp v102, v55, v55 row_ror:8 row_mask:0xf bank_mask:0x3
	v_add_f32_dpp v103, v103, v103 row_ror:8 row_mask:0xf bank_mask:0xc
	v_add_f32_dpp v103, v56, v56 row_ror:8 row_mask:0xf bank_mask:0x3
	v_add_f32_dpp v104, v104, v104 row_ror:8 row_mask:0xf bank_mask:0xc
	v_add_f32_dpp v104, v57, v57 row_ror:8 row_mask:0xf bank_mask:0x3
	v_add_f32_dpp v105, v105, v105 row_ror:8 row_mask:0xf bank_mask:0xc
	v_add_f32_dpp v105, v81, v81 row_ror:8 row_mask:0xf bank_mask:0x3
	v_add_f32_dpp v61, v61, v61 row_ror:8 row_mask:0xf bank_mask:0xc
	v_add_f32_dpp v61, v82, v82 row_ror:8 row_mask:0xf bank_mask:0x3
	v_add_f32_dpp v103, v103, v103 row_ror:4 row_mask:0xf bank_mask:0xa
	v_add_f32_dpp v103, v83, v83 row_ror:12 row_mask:0xf bank_mask:0x5
	v_add_f32_dpp v104, v104, v104 row_ror:4 row_mask:0xf bank_mask:0xa
	v_add_f32_dpp v104, v100, v100 row_ror:12 row_mask:0xf bank_mask:0x5
	v_add_f32_dpp v105, v105, v105 row_ror:4 row_mask:0xf bank_mask:0xa
	v_add_f32_dpp v105, v101, v101 row_ror:12 row_mask:0xf bank_mask:0x5
	v_add_f32_dpp v61, v61, v61 row_ror:4 row_mask:0xf bank_mask:0xa
	v_add_f32_dpp v61, v102, v102 row_ror:12 row_mask:0xf bank_mask:0x5
	v_cndmask_b32_e64 v62, v105, v103, s[38:39]
	v_cndmask_b32_e64 v63, v103, v105, s[38:39]
	v_cndmask_b32_e64 v64, v61, v104, s[38:39]
	v_cndmask_b32_e64 v65, v104, v61, s[38:39]
	v_add_f32_dpp v62, v63, v62 quad_perm:[2,3,0,1] row_mask:0xf bank_mask:0xf bound_ctrl:1
	s_nop 0
	v_add_f32_dpp v63, v65, v64 quad_perm:[2,3,0,1] row_mask:0xf bank_mask:0xf bound_ctrl:1
	v_cndmask_b32_e64 v65, v63, v62, s[40:41]
	v_cndmask_b32_e64 v62, v62, v63, s[40:41]
	s_nop 1
	v_add_f32_dpp v62, v62, v65 quad_perm:[1,0,3,2] row_mask:0xf bank_mask:0xf bound_ctrl:1
	v_cvt_pk_bf16_f32 v62, v62, v62
	global_store_short v[2:3], v62, off
	s_cmp_lg_u32 s28, 0x800000
	s_cbranch_scc1 .Lscan_cons_chunk
	s_branch .LBB0_53
